# unit-boundary relaxed waits: first two counted waits of a unit's first K-iteration allow the previous epilogue's 16 stores in flight (up/gin/foxin)
# baseline (speedup 1.0000x reference)
; #define PG8_STAGE(bufoff, gbase, voff) do { _Pragma("unroll") for (int _i = 0; _i < 2; ++_i) \
;         __builtin_amdgcn_global_load_lds((const unsigned*)((const char*)(gbase) + (voff)[_i]), (PG8_LAS unsigned*)(lds + (bufoff) + ldsw + _i * 8192), 16, 0, 0); } while (0)
; #define PG8_LDA(dst, b, h) do { _Pragma("unroll") for (int m = 0; m < 4; ++m) _Pragma("unroll") for (int k = 0; k < 2; ++k) dst[m][k] = *(const PG8_LAS bf16x8*)(lds + PG8_SA(b, h) + aoff + m * 2048 + k * 1024); } while (0)
; #define PG8_LDB(dst, b, h) do { _Pragma("unroll") for (int n = 0; n < 2; ++n) _Pragma("unroll") for (int k = 0; k < 2; ++k) dst[n][k] = *(const PG8_LAS bf16x8*)(lds + PG8_SB(b, h) + boff + n * 2048 + k * 1024); } while (0)
; #define PG8_WAIT_V(n) asm volatile("s_waitcnt vmcnt(" #n ")" ::: "memory")
; #define PG8_WAIT_L(n) asm volatile("s_waitcnt lgkmcnt(" #n ")" ::: "memory")
; #define PG8_BAR __builtin_amdgcn_s_barrier()
; #define PG8_SCHED __builtin_amdgcn_sched_barrier(0)
; template <class Epi, class Sched, bool ALIGN_EPI = false, bool SP2 = false>
; __device__ __forceinline__ void gemm_phase(PG8_LAS unsigned char* lds, const Gemm g, const Sched& S, const Epi& E, const int tid_in) {
;     ...
;         const char* nA = has_next ? (const char*)g.A + (size_t)nxt.pm * tstepA + (size_t)(nxt.pm >> 3) * g.abx : cA; const char* nB = has_next ? (const char*)g.Bt + (size_t)nxt.pn * tstepB : cB;
;         for (int t = 0; t < nt; t += 2) {
;             const bool last = (t == nt - 2);
;             const char* a1 = cA + (size_t)(t + 1) * kstep;
;             const char* a2 = last ? nA : cA + (size_t)(t + 2) * kstep; const char* b2 = last ? nB : cB + (size_t)(t + 2) * kstep;
;             const char* a3 = a2 + kstep; const char* b3 = b2 + kstep;
;             if (last && has_next) S.a_ready(nxt);
;             if constexpr (SP2) {
;             PG8_LDB(B0, 0, 0); PG8_LDB(B1, 0, 1); PG8_SCHED; PG8_LDA(At, 0, 0); PG8_STAGE(PG8_SA(1, 1), a1 + hstepA, voffA);
;             PG8_WAIT_V(8); PG8_WAIT_L(0); PG8_BAR; PG8_MMA(0, 0, At, B0); PG8_MMA(0, 1, At, B1); PG8_BAR; PG8_SCHED;
;     ...
;         for (int a = 0; a < 2; ++a)
; #pragma unroll
;             for (int b = 0; b < 2; ++b)
; #pragma unroll
;                 for (int m = 0; m < 4; ++m)
; #pragma unroll
;                     for (int n = 0; n < 2; ++n) acc[a][b][m][n] = (f32x4){0.f, 0.f, 0.f, 0.f};
.LBB0_223:
	s_ashr_i32 s57, s56, 31
	s_lshl_b64 s[4:5], s[56:57], 19
	s_add_u32 s58, s26, s4
	s_addc_u32 s59, s27, s5
	s_and_b64 s[4:5], s[40:41], exec
	s_cselect_b32 s57, s59, s1
	s_cselect_b32 s71, s58, s0
	s_ashr_i32 s55, s54, 31
	s_lshl_b64 s[4:5], s[54:55], 19
	s_add_u32 s60, s22, s4
	s_addc_u32 s61, s23, s5
	s_and_b64 s[4:5], s[40:41], exec
	s_cselect_b32 s55, s61, s21
	s_cselect_b32 s72, s60, s20
	s_add_u32 s0, s0, 0x40080
	s_addc_u32 s1, s1, 0
	s_add_u32 s73, s20, 0x100
	v_mov_b32_e32 v0, 0
	s_addc_u32 s74, s21, 0
	s_mov_b32 s75, -2
	s_cmp_gt_u32 s66, 1
	s_cselect_b32 s101, 1, 0
	v_mov_b32_e32 v1, v0
	v_mov_b32_e32 v2, v0
	v_mov_b32_e32 v3, v0
	v_mov_b32_e32 v4, v0
	v_mov_b32_e32 v5, v0
	v_mov_b32_e32 v6, v0
	v_mov_b32_e32 v7, v0
	v_mov_b32_e32 v16, v0
	v_mov_b32_e32 v17, v0
	v_mov_b32_e32 v18, v0
	v_mov_b32_e32 v19, v0
	v_mov_b32_e32 v20, v0
	v_mov_b32_e32 v21, v0
	v_mov_b32_e32 v22, v0
	v_mov_b32_e32 v23, v0
	v_mov_b32_e32 v32, v0
	v_mov_b32_e32 v33, v0
	v_mov_b32_e32 v34, v0
	v_mov_b32_e32 v35, v0
	v_mov_b32_e32 v36, v0
	v_mov_b32_e32 v37, v0
	v_mov_b32_e32 v38, v0
	v_mov_b32_e32 v39, v0
	v_mov_b32_e32 v48, v0
	v_mov_b32_e32 v49, v0
	v_mov_b32_e32 v50, v0
	v_mov_b32_e32 v51, v0
	v_mov_b32_e32 v52, v0
	v_mov_b32_e32 v53, v0
	v_mov_b32_e32 v54, v0
	v_mov_b32_e32 v55, v0
	v_mov_b32_e32 v8, v0
	v_mov_b32_e32 v9, v0
	v_mov_b32_e32 v10, v0
	v_mov_b32_e32 v11, v0
	v_mov_b32_e32 v12, v0
	v_mov_b32_e32 v13, v0
	v_mov_b32_e32 v14, v0
	v_mov_b32_e32 v15, v0
	v_mov_b32_e32 v24, v0
	v_mov_b32_e32 v25, v0
	v_mov_b32_e32 v26, v0
	v_mov_b32_e32 v27, v0
	v_mov_b32_e32 v28, v0
	v_mov_b32_e32 v29, v0
	v_mov_b32_e32 v30, v0
	v_mov_b32_e32 v31, v0
	v_mov_b32_e32 v40, v0
	v_mov_b32_e32 v41, v0
	v_mov_b32_e32 v42, v0
	v_mov_b32_e32 v43, v0
	v_mov_b32_e32 v44, v0
	v_mov_b32_e32 v45, v0
	v_mov_b32_e32 v46, v0
	v_mov_b32_e32 v47, v0
	v_mov_b32_e32 v56, v0
	v_mov_b32_e32 v57, v0
	v_mov_b32_e32 v58, v0
	v_mov_b32_e32 v59, v0
	v_mov_b32_e32 v60, v0
	v_mov_b32_e32 v61, v0
	v_mov_b32_e32 v62, v0
	v_mov_b32_e32 v63, v0
	v_mov_b32_e32 v64, v0
	v_mov_b32_e32 v65, v0
	v_mov_b32_e32 v66, v0
	v_mov_b32_e32 v67, v0
	v_mov_b32_e32 v68, v0
	v_mov_b32_e32 v69, v0
	v_mov_b32_e32 v70, v0
	v_mov_b32_e32 v71, v0
	v_mov_b32_e32 v80, v0
	v_mov_b32_e32 v81, v0
	v_mov_b32_e32 v82, v0
	v_mov_b32_e32 v83, v0
	v_mov_b32_e32 v84, v0
	v_mov_b32_e32 v85, v0
	v_mov_b32_e32 v86, v0
	v_mov_b32_e32 v87, v0
	v_mov_b32_e32 v96, v0
	v_mov_b32_e32 v97, v0
	v_mov_b32_e32 v98, v0
	v_mov_b32_e32 v99, v0
	v_mov_b32_e32 v100, v0
	v_mov_b32_e32 v101, v0
	v_mov_b32_e32 v102, v0
	v_mov_b32_e32 v103, v0
	v_mov_b32_e32 v116, v0
	v_mov_b32_e32 v117, v0
	v_mov_b32_e32 v118, v0
	v_mov_b32_e32 v119, v0
	v_mov_b32_e32 v120, v0
	v_mov_b32_e32 v121, v0
	v_mov_b32_e32 v122, v0
	v_mov_b32_e32 v123, v0
	v_mov_b32_e32 v72, v0
	v_mov_b32_e32 v73, v0
	v_mov_b32_e32 v74, v0
	v_mov_b32_e32 v75, v0
	v_mov_b32_e32 v76, v0
	v_mov_b32_e32 v77, v0
	v_mov_b32_e32 v78, v0
	v_mov_b32_e32 v79, v0
	v_mov_b32_e32 v88, v0
	v_mov_b32_e32 v89, v0
	v_mov_b32_e32 v90, v0
	v_mov_b32_e32 v91, v0
	v_mov_b32_e32 v92, v0
	v_mov_b32_e32 v93, v0
	v_mov_b32_e32 v94, v0
	v_mov_b32_e32 v95, v0
	v_mov_b32_e32 v104, v0
	v_mov_b32_e32 v105, v0
	v_mov_b32_e32 v106, v0
	v_mov_b32_e32 v107, v0
	v_mov_b32_e32 v108, v0
	v_mov_b32_e32 v109, v0
	v_mov_b32_e32 v110, v0
	v_mov_b32_e32 v111, v0
	v_mov_b32_e32 v124, v0
	v_mov_b32_e32 v125, v0
	v_mov_b32_e32 v126, v0
	v_mov_b32_e32 v127, v0
	v_mov_b32_e32 v128, v0
	v_mov_b32_e32 v129, v0
	v_mov_b32_e32 v130, v0
	v_mov_b32_e32 v131, v0
.LBB0_224:
	s_add_u32 s4, s0, 0xfffc0080
	s_addc_u32 s5, s1, -1
	s_add_i32 s76, 0, 0x10000
	s_cmp_eq_u32 s75, 12
	s_cselect_b32 s21, s57, s5
	s_cselect_b32 s20, s71, s4
	v_add_u32_e32 v114, s76, v171
	s_cselect_b32 s5, s55, s74
	s_cselect_b32 s4, s72, s73
	s_add_i32 s78, 0, 0x14000
	ds_read_b128 v[132:135], v114
	ds_read_b128 v[136:139], v114 offset:1024
	ds_read_b128 v[140:143], v114 offset:2048
	s_waitcnt lgkmcnt(0)
	ds_read_b128 v[154:157], v114 offset:3072
	v_add_u32_e32 v114, s78, v171
	ds_read_b128 v[158:161], v114
	ds_read_b128 v[162:165], v114 offset:1024
	ds_read_b128 v[166:169], v114 offset:2048
	ds_read_b128 v[200:203], v114 offset:3072
	v_lshl_add_u64 v[230:231], s[0:1], 0, v[150:151]
	s_add_i32 m0, s28, 0xc000
	ds_read_b128 v[204:207], v197
	ds_read_b128 v[208:211], v197 offset:1024
	ds_read_b128 v[212:215], v197 offset:2048
	ds_read_b128 v[216:219], v197 offset:3072
	ds_read_b128 v[220:223], v197 offset:4096
	ds_read_b128 v[224:227], v197 offset:5120
	ds_read_b128 v[238:241], v197 offset:6144
	ds_read_b128 v[242:245], v197 offset:7168
	global_load_lds_dwordx4 v[230:231], off
	v_lshl_add_u64 v[230:231], s[0:1], 0, v[152:153]
	s_add_i32 m0, s28, 0xe000
	s_nop 0
	global_load_lds_dwordx4 v[230:231], off
	s_cmp_lg_u32 s101, 0
	s_cbranch_scc1 .Lmy_rw_foxin_0r
	s_waitcnt vmcnt(8)
	s_branch .Lmy_rw_foxin_0j
; #define PG8_STAGE(bufoff, gbase, voff) do { _Pragma("unroll") for (int _i = 0; _i < 2; ++_i) \
;         __builtin_amdgcn_global_load_lds((const unsigned*)((const char*)(gbase) + (voff)[_i]), (PG8_LAS unsigned*)(lds + (bufoff) + ldsw + _i * 8192), 16, 0, 0); } while (0)
; #define PG8_LDA(dst, b, h) do { _Pragma("unroll") for (int m = 0; m < 4; ++m) _Pragma("unroll") for (int k = 0; k < 2; ++k) dst[m][k] = *(const PG8_LAS bf16x8*)(lds + PG8_SA(b, h) + aoff + m * 2048 + k * 1024); } while (0)
; #define PG8_MMA(ai, bj, At, Bt) do { __builtin_amdgcn_s_setprio(1); _Pragma("unroll") for (int m = 0; m < 4; ++m) _Pragma("unroll") for (int n = 0; n < 2; ++n) _Pragma("unroll") for (int k = 0; k < 2; ++k) \
;         acc[ai][bj][m][n] = __builtin_amdgcn_mfma_f32_16x16x32_bf16(Bt[n][k], At[m][k], acc[ai][bj][m][n], 0, 0, 0); __builtin_amdgcn_s_setprio(0); } while (0)
; #define PG8_WAIT_V(n) asm volatile("s_waitcnt vmcnt(" #n ")" ::: "memory")
; #define PG8_WAIT_L(n) asm volatile("s_waitcnt lgkmcnt(" #n ")" ::: "memory")
; #define PG8_BAR __builtin_amdgcn_s_barrier()
; #define PG8_SCHED __builtin_amdgcn_sched_barrier(0)
; template <class Epi, class Sched, bool ALIGN_EPI = false, bool SP2 = false>
; __device__ __forceinline__ void gemm_phase(PG8_LAS unsigned char* lds, const Gemm g, const Sched& S, const Epi& E, const int tid_in) {
;     ...
;             PG8_WAIT_V(8); PG8_WAIT_L(0); PG8_BAR; PG8_MMA(0, 0, At, B0); PG8_MMA(0, 1, At, B1); PG8_BAR; PG8_SCHED;
;             PG8_LDA(At, 0, 1); PG8_STAGE(PG8_SB(0, 0), b2, voffB); PG8_STAGE(PG8_SB(0, 1), b2 + hstepB, voffB); PG8_STAGE(PG8_SA(0, 0), a2, voffA);
;             PG8_WAIT_V(8); PG8_WAIT_L(0); PG8_BAR; PG8_MMA(1, 0, At, B0); PG8_MMA(1, 1, At, B1); PG8_BAR; PG8_SCHED;
.Lmy_rw_foxin_0r:
	s_waitcnt vmcnt(24)
.Lmy_rw_foxin_0j:
	s_waitcnt lgkmcnt(0)
	s_barrier
	s_setprio 1
	s_waitcnt lgkmcnt(0)
	v_mfma_f32_16x16x32_bf16 v[128:131], v[132:135], v[204:207], v[128:131]
	v_mfma_f32_16x16x32_bf16 v[124:127], v[140:143], v[204:207], v[124:127]
	v_mfma_f32_16x16x32_bf16 v[108:111], v[132:135], v[212:215], v[108:111]
	v_mfma_f32_16x16x32_bf16 v[104:107], v[140:143], v[212:215], v[104:107]
	v_mfma_f32_16x16x32_bf16 v[92:95], v[132:135], v[220:223], v[92:95]
	v_mfma_f32_16x16x32_bf16 v[88:91], v[140:143], v[220:223], v[88:91]
	v_mfma_f32_16x16x32_bf16 v[76:79], v[132:135], v[238:241], v[76:79]
	v_mfma_f32_16x16x32_bf16 v[72:75], v[140:143], v[238:241], v[72:75]
	v_mfma_f32_16x16x32_bf16 v[128:131], v[136:139], v[208:211], v[128:131]
	v_mfma_f32_16x16x32_bf16 v[124:127], v[154:157], v[208:211], v[124:127]
	v_mfma_f32_16x16x32_bf16 v[108:111], v[136:139], v[216:219], v[108:111]
	v_mfma_f32_16x16x32_bf16 v[104:107], v[154:157], v[216:219], v[104:107]
	v_mfma_f32_16x16x32_bf16 v[92:95], v[136:139], v[224:227], v[92:95]
	v_mfma_f32_16x16x32_bf16 v[88:91], v[154:157], v[224:227], v[88:91]
	v_mfma_f32_16x16x32_bf16 v[76:79], v[136:139], v[242:245], v[76:79]
	v_mfma_f32_16x16x32_bf16 v[72:75], v[154:157], v[242:245], v[72:75]
	s_setprio 0
	s_setprio 1
	v_mfma_f32_16x16x32_bf16 v[120:123], v[158:161], v[204:207], v[120:123]
	v_mfma_f32_16x16x32_bf16 v[116:119], v[166:169], v[204:207], v[116:119]
	v_mfma_f32_16x16x32_bf16 v[100:103], v[158:161], v[212:215], v[100:103]
	v_mfma_f32_16x16x32_bf16 v[96:99], v[166:169], v[212:215], v[96:99]
	v_mfma_f32_16x16x32_bf16 v[84:87], v[158:161], v[220:223], v[84:87]
	v_mfma_f32_16x16x32_bf16 v[80:83], v[166:169], v[220:223], v[80:83]
	v_mfma_f32_16x16x32_bf16 v[68:71], v[158:161], v[238:241], v[68:71]
	v_mfma_f32_16x16x32_bf16 v[64:67], v[166:169], v[238:241], v[64:67]
	v_mfma_f32_16x16x32_bf16 v[120:123], v[162:165], v[208:211], v[120:123]
	v_mfma_f32_16x16x32_bf16 v[116:119], v[200:203], v[208:211], v[116:119]
	v_mfma_f32_16x16x32_bf16 v[100:103], v[162:165], v[216:219], v[100:103]
	v_mfma_f32_16x16x32_bf16 v[96:99], v[200:203], v[216:219], v[96:99]
	v_mfma_f32_16x16x32_bf16 v[84:87], v[162:165], v[224:227], v[84:87]
	v_mfma_f32_16x16x32_bf16 v[80:83], v[200:203], v[224:227], v[80:83]
	v_mfma_f32_16x16x32_bf16 v[68:71], v[162:165], v[242:245], v[68:71]
	v_mfma_f32_16x16x32_bf16 v[64:67], v[200:203], v[242:245], v[64:67]
	s_setprio 0
	s_barrier
	s_add_i32 s76, s76, s19
	v_lshl_add_u64 v[230:231], s[4:5], 0, v[144:145]
	s_mov_b32 m0, s76
	ds_read_b128 v[204:207], v197 offset:16384
	ds_read_b128 v[208:211], v197 offset:17408
	ds_read_b128 v[212:215], v197 offset:18432
	ds_read_b128 v[216:219], v197 offset:19456
	ds_read_b128 v[220:223], v197 offset:20480
	ds_read_b128 v[224:227], v197 offset:21504
	ds_read_b128 v[238:241], v197 offset:22528
	ds_read_b128 v[242:245], v197 offset:23552
	global_load_lds_dwordx4 v[230:231], off
	s_add_i32 m0, s76, 0x2000
	s_add_u32 s76, s4, 0x40000
	v_lshl_add_u64 v[234:235], s[4:5], 0, v[148:149]
	s_addc_u32 s77, s5, 0
	s_add_i32 s78, s78, s19
	global_load_lds_dwordx4 v[234:235], off
	v_lshl_add_u64 v[246:247], s[76:77], 0, v[144:145]
	s_mov_b32 m0, s78
	v_lshl_add_u64 v[248:249], s[20:21], 0, v[146:147]
	global_load_lds_dwordx4 v[246:247], off
	v_lshl_add_u64 v[246:247], s[76:77], 0, v[148:149]
	s_add_i32 m0, s78, 0x2000
	s_nop 0
	global_load_lds_dwordx4 v[246:247], off
	v_lshl_add_u64 v[246:247], s[20:21], 0, v[112:113]
	s_mov_b32 m0, s28
	s_nop 0
	global_load_lds_dwordx4 v[246:247], off
	s_mov_b32 m0, s29
	s_nop 0
	global_load_lds_dwordx4 v[248:249], off
	s_cmp_lg_u32 s101, 0
	s_cbranch_scc1 .Lmy_rw_foxin_1r
	s_waitcnt vmcnt(8)
	s_branch .Lmy_rw_foxin_1j

; #define PG8_STAGE(bufoff, gbase, voff) do { _Pragma("unroll") for (int _i = 0; _i < 2; ++_i) \
;         __builtin_amdgcn_global_load_lds((const unsigned*)((const char*)(gbase) + (voff)[_i]), (PG8_LAS unsigned*)(lds + (bufoff) + ldsw + _i * 8192), 16, 0, 0); } while (0)
; #define PG8_LDA(dst, b, h) do { _Pragma("unroll") for (int m = 0; m < 4; ++m) _Pragma("unroll") for (int k = 0; k < 2; ++k) dst[m][k] = *(const PG8_LAS bf16x8*)(lds + PG8_SA(b, h) + aoff + m * 2048 + k * 1024); } while (0)
; #define PG8_LDB(dst, b, h) do { _Pragma("unroll") for (int n = 0; n < 2; ++n) _Pragma("unroll") for (int k = 0; k < 2; ++k) dst[n][k] = *(const PG8_LAS bf16x8*)(lds + PG8_SB(b, h) + boff + n * 2048 + k * 1024); } while (0)
; #define PG8_MMA(ai, bj, At, Bt) do { __builtin_amdgcn_s_setprio(1); _Pragma("unroll") for (int m = 0; m < 4; ++m) _Pragma("unroll") for (int n = 0; n < 2; ++n) _Pragma("unroll") for (int k = 0; k < 2; ++k) \
;         acc[ai][bj][m][n] = __builtin_amdgcn_mfma_f32_16x16x32_bf16(Bt[n][k], At[m][k], acc[ai][bj][m][n], 0, 0, 0); __builtin_amdgcn_s_setprio(0); } while (0)
; #define PG8_WAIT_V(n) asm volatile("s_waitcnt vmcnt(" #n ")" ::: "memory")
; #define PG8_WAIT_L(n) asm volatile("s_waitcnt lgkmcnt(" #n ")" ::: "memory")
; #define PG8_BAR __builtin_amdgcn_s_barrier()
; #define PG8_SCHED __builtin_amdgcn_sched_barrier(0)
; template <class Epi, class Sched, bool ALIGN_EPI = false, bool SP2 = false>
; __device__ __forceinline__ void gemm_phase(PG8_LAS unsigned char* lds, const Gemm g, const Sched& S, const Epi& E, const int tid_in) {
;     ...
;             PG8_WAIT_V(8); PG8_WAIT_L(0); PG8_BAR; PG8_MMA(1, 0, At, B0); PG8_MMA(1, 1, At, B1); PG8_BAR; PG8_SCHED;
;             PG8_LDB(B0, 1, 0); PG8_LDB(B1, 1, 1); PG8_SCHED; PG8_LDA(At, 1, 0); PG8_STAGE(PG8_SA(0, 1), a2 + hstepA, voffA);
;             PG8_WAIT_V(8); PG8_WAIT_L(0); PG8_BAR; PG8_MMA(0, 0, At, B0); PG8_MMA(0, 1, At, B1); PG8_BAR; PG8_SCHED;
.Lmy_rw_foxin_1j:
	s_mov_b32 s101, 0
	s_waitcnt lgkmcnt(0)
	s_barrier
	s_setprio 1
	s_waitcnt lgkmcnt(0)
	v_mfma_f32_16x16x32_bf16 v[60:63], v[132:135], v[204:207], v[60:63]
	v_mfma_f32_16x16x32_bf16 v[56:59], v[140:143], v[204:207], v[56:59]
	v_mfma_f32_16x16x32_bf16 v[44:47], v[132:135], v[212:215], v[44:47]
	v_mfma_f32_16x16x32_bf16 v[40:43], v[140:143], v[212:215], v[40:43]
	v_mfma_f32_16x16x32_bf16 v[28:31], v[132:135], v[220:223], v[28:31]
	v_mfma_f32_16x16x32_bf16 v[24:27], v[140:143], v[220:223], v[24:27]
	v_mfma_f32_16x16x32_bf16 v[12:15], v[132:135], v[238:241], v[12:15]
	v_mfma_f32_16x16x32_bf16 v[8:11], v[140:143], v[238:241], v[8:11]
	v_mfma_f32_16x16x32_bf16 v[60:63], v[136:139], v[208:211], v[60:63]
	v_mfma_f32_16x16x32_bf16 v[56:59], v[154:157], v[208:211], v[56:59]
	v_mfma_f32_16x16x32_bf16 v[44:47], v[136:139], v[216:219], v[44:47]
	v_mfma_f32_16x16x32_bf16 v[40:43], v[154:157], v[216:219], v[40:43]
	v_mfma_f32_16x16x32_bf16 v[28:31], v[136:139], v[224:227], v[28:31]
	v_mfma_f32_16x16x32_bf16 v[24:27], v[154:157], v[224:227], v[24:27]
	v_mfma_f32_16x16x32_bf16 v[12:15], v[136:139], v[242:245], v[12:15]
	v_mfma_f32_16x16x32_bf16 v[8:11], v[154:157], v[242:245], v[8:11]
	s_setprio 0
	s_setprio 1
	v_mfma_f32_16x16x32_bf16 v[52:55], v[158:161], v[204:207], v[52:55]
	v_mfma_f32_16x16x32_bf16 v[48:51], v[166:169], v[204:207], v[48:51]
	v_mfma_f32_16x16x32_bf16 v[36:39], v[158:161], v[212:215], v[36:39]
	v_mfma_f32_16x16x32_bf16 v[32:35], v[166:169], v[212:215], v[32:35]
	v_mfma_f32_16x16x32_bf16 v[20:23], v[158:161], v[220:223], v[20:23]
	v_mfma_f32_16x16x32_bf16 v[16:19], v[166:169], v[220:223], v[16:19]
	v_mfma_f32_16x16x32_bf16 v[4:7], v[158:161], v[238:241], v[4:7]
	v_mfma_f32_16x16x32_bf16 v[0:3], v[166:169], v[238:241], v[0:3]
	v_mfma_f32_16x16x32_bf16 v[52:55], v[162:165], v[208:211], v[52:55]
	v_mfma_f32_16x16x32_bf16 v[48:51], v[200:203], v[208:211], v[48:51]
	v_mfma_f32_16x16x32_bf16 v[36:39], v[162:165], v[216:219], v[36:39]
	v_mfma_f32_16x16x32_bf16 v[32:35], v[200:203], v[216:219], v[32:35]
	v_mfma_f32_16x16x32_bf16 v[20:23], v[162:165], v[224:227], v[20:23]
	v_mfma_f32_16x16x32_bf16 v[16:19], v[200:203], v[224:227], v[16:19]
	v_mfma_f32_16x16x32_bf16 v[4:7], v[162:165], v[242:245], v[4:7]
	v_mfma_f32_16x16x32_bf16 v[0:3], v[200:203], v[242:245], v[0:3]
	s_setprio 0
	s_barrier
	s_add_i32 s76, 0, 0x18000
	v_add_u32_e32 v114, s76, v171
	s_add_i32 s77, 0, 0x1c000
	ds_read_b128 v[132:135], v114
	ds_read_b128 v[136:139], v114 offset:1024
	ds_read_b128 v[140:143], v114 offset:2048
	ds_read_b128 v[154:157], v114 offset:3072
	v_add_u32_e32 v114, s77, v171
	ds_read_b128 v[158:161], v114
	ds_read_b128 v[162:165], v114 offset:1024
	ds_read_b128 v[166:169], v114 offset:2048
	ds_read_b128 v[200:203], v114 offset:3072
	s_add_u32 s20, s20, 0x40000
	s_addc_u32 s21, s21, 0
	s_mov_b32 m0, s62
	v_lshl_add_u64 v[250:251], s[20:21], 0, v[112:113]
	ds_read_b128 v[204:207], v197 offset:32768
	ds_read_b128 v[208:211], v197 offset:33792
	ds_read_b128 v[212:215], v197 offset:34816
	ds_read_b128 v[216:219], v197 offset:35840
	ds_read_b128 v[220:223], v197 offset:36864
	ds_read_b128 v[224:227], v197 offset:37888
	ds_read_b128 v[238:241], v197 offset:38912
	ds_read_b128 v[242:245], v197 offset:39936
	global_load_lds_dwordx4 v[250:251], off
	v_lshl_add_u64 v[250:251], s[20:21], 0, v[146:147]
	s_mov_b32 m0, s63
	s_nop 0
	global_load_lds_dwordx4 v[250:251], off
	s_waitcnt vmcnt(8)
	s_waitcnt lgkmcnt(0)
	s_barrier
	s_setprio 1
	s_waitcnt lgkmcnt(0)
	v_mfma_f32_16x16x32_bf16 v[128:131], v[132:135], v[204:207], v[128:131]
	v_mfma_f32_16x16x32_bf16 v[124:127], v[140:143], v[204:207], v[124:127]
	v_mfma_f32_16x16x32_bf16 v[108:111], v[132:135], v[212:215], v[108:111]
	v_mfma_f32_16x16x32_bf16 v[104:107], v[140:143], v[212:215], v[104:107]
	v_mfma_f32_16x16x32_bf16 v[92:95], v[132:135], v[220:223], v[92:95]
	v_mfma_f32_16x16x32_bf16 v[88:91], v[140:143], v[220:223], v[88:91]
	v_mfma_f32_16x16x32_bf16 v[76:79], v[132:135], v[238:241], v[76:79]
	v_mfma_f32_16x16x32_bf16 v[72:75], v[140:143], v[238:241], v[72:75]
	v_mfma_f32_16x16x32_bf16 v[128:131], v[136:139], v[208:211], v[128:131]
	v_mfma_f32_16x16x32_bf16 v[124:127], v[154:157], v[208:211], v[124:127]
	v_mfma_f32_16x16x32_bf16 v[108:111], v[136:139], v[216:219], v[108:111]
	v_mfma_f32_16x16x32_bf16 v[104:107], v[154:157], v[216:219], v[104:107]
	v_mfma_f32_16x16x32_bf16 v[92:95], v[136:139], v[224:227], v[92:95]
	v_mfma_f32_16x16x32_bf16 v[88:91], v[154:157], v[224:227], v[88:91]
	v_mfma_f32_16x16x32_bf16 v[76:79], v[136:139], v[242:245], v[76:79]
	v_mfma_f32_16x16x32_bf16 v[72:75], v[154:157], v[242:245], v[72:75]
	s_setprio 0
	s_setprio 1
	v_mfma_f32_16x16x32_bf16 v[120:123], v[158:161], v[204:207], v[120:123]
	v_mfma_f32_16x16x32_bf16 v[116:119], v[166:169], v[204:207], v[116:119]
	v_mfma_f32_16x16x32_bf16 v[100:103], v[158:161], v[212:215], v[100:103]
	v_mfma_f32_16x16x32_bf16 v[96:99], v[166:169], v[212:215], v[96:99]
	v_mfma_f32_16x16x32_bf16 v[84:87], v[158:161], v[220:223], v[84:87]
	v_mfma_f32_16x16x32_bf16 v[80:83], v[166:169], v[220:223], v[80:83]
	v_mfma_f32_16x16x32_bf16 v[68:71], v[158:161], v[238:241], v[68:71]
	v_mfma_f32_16x16x32_bf16 v[64:67], v[166:169], v[238:241], v[64:67]
	v_mfma_f32_16x16x32_bf16 v[120:123], v[162:165], v[208:211], v[120:123]
	v_mfma_f32_16x16x32_bf16 v[116:119], v[200:203], v[208:211], v[116:119]
	v_mfma_f32_16x16x32_bf16 v[100:103], v[162:165], v[216:219], v[100:103]
	v_mfma_f32_16x16x32_bf16 v[96:99], v[200:203], v[216:219], v[96:99]
	v_mfma_f32_16x16x32_bf16 v[84:87], v[162:165], v[224:227], v[84:87]
	v_mfma_f32_16x16x32_bf16 v[80:83], v[200:203], v[224:227], v[80:83]
	v_mfma_f32_16x16x32_bf16 v[68:71], v[162:165], v[242:245], v[68:71]
	v_mfma_f32_16x16x32_bf16 v[64:67], v[200:203], v[242:245], v[64:67]
	s_setprio 0
	s_barrier
; #define PG8_STAGE(bufoff, gbase, voff) do { _Pragma("unroll") for (int _i = 0; _i < 2; ++_i) \
;         __builtin_amdgcn_global_load_lds((const unsigned*)((const char*)(gbase) + (voff)[_i]), (PG8_LAS unsigned*)(lds + (bufoff) + ldsw + _i * 8192), 16, 0, 0); } while (0)
; #define PG8_LDA(dst, b, h) do { _Pragma("unroll") for (int m = 0; m < 4; ++m) _Pragma("unroll") for (int k = 0; k < 2; ++k) dst[m][k] = *(const PG8_LAS bf16x8*)(lds + PG8_SA(b, h) + aoff + m * 2048 + k * 1024); } while (0)
; #define PG8_BAR __builtin_amdgcn_s_barrier()
; template <class Epi, class Sched, bool ALIGN_EPI = false, bool SP2 = false>
; __device__ __forceinline__ void gemm_phase(PG8_LAS unsigned char* lds, const Gemm g, const Sched& S, const Epi& E, const int tid_in) {
;     ...
;             PG8_LDA(At, 1, 1); PG8_STAGE(PG8_SB(1, 0), b3, voffB); PG8_STAGE(PG8_SB(1, 1), b3 + hstepB, voffB); PG8_STAGE(PG8_SA(1, 0), a3, voffA);
;             PG8_WAIT_V(8); PG8_WAIT_L(0); PG8_BAR; PG8_MMA(1, 0, At, B0); PG8_MMA(1, 1, At, B1); PG8_BAR; PG8_SCHED;
;             } else {
;             PG8_LDB(B0, 0, 0); PG8_SCHED; PG8_LDA(At, 0, 0); PG8_STAGE(PG8_SA(1, 1), a1 + hstepA, voffA);
;             PG8_WAIT_L(8); PG8_BAR; PG8_WAIT_L(0); PG8_MMA(0, 0, At, B0); PG8_BAR; PG8_SCHED;
;             PG8_LDB(B1, 0, 1); PG8_STAGE(PG8_SB(0, 0), b2, voffB);
;             PG8_BAR; PG8_WAIT_L(0); PG8_MMA(0, 1, At, B1); PG8_BAR;
;             PG8_LDA(At, 0, 1); PG8_STAGE(PG8_SA(0, 0), a2, voffA);
;             PG8_BAR; PG8_WAIT_L(0); PG8_MMA(1, 0, At, B0); PG8_BAR; PG8_SCHED;
;             PG8_STAGE(PG8_SB(0, 1), b2 + hstepB, voffB);
;             PG8_WAIT_V(6); PG8_BAR; PG8_MMA(1, 1, At, B1); PG8_BAR;
;             PG8_LDB(B0, 1, 0); PG8_SCHED; PG8_LDA(At, 1, 0); PG8_STAGE(PG8_SA(0, 1), a2 + hstepA, voffA);
;             PG8_WAIT_L(8); PG8_BAR; PG8_WAIT_L(0); PG8_MMA(0, 0, At, B0); PG8_BAR; PG8_SCHED;
;             PG8_LDB(B1, 1, 1); PG8_STAGE(PG8_SB(1, 0), b3, voffB);
;             PG8_BAR; PG8_WAIT_L(0); PG8_MMA(0, 1, At, B1); PG8_BAR;
;             PG8_LDA(At, 1, 1); PG8_STAGE(PG8_SA(1, 0), a3, voffA);
;             PG8_BAR; PG8_WAIT_L(0); PG8_MMA(1, 0, At, B0); PG8_BAR; PG8_SCHED;
;             PG8_STAGE(PG8_SB(1, 1), b3 + hstepB, voffB);
;             PG8_WAIT_V(6); PG8_BAR; PG8_MMA(1, 1, At, B1); PG8_BAR;
;             }
;         }
;         if constexpr (ALIGN_EPI) { if (wr == 0) PG8_BAR; }
	s_add_i32 s20, s76, s19
	v_lshl_add_u64 v[230:231], v[230:231], 0, s[10:11]
	s_mov_b32 m0, s20
	ds_read_b128 v[204:207], v197 offset:49152
	ds_read_b128 v[208:211], v197 offset:50176
	ds_read_b128 v[212:215], v197 offset:51200
	ds_read_b128 v[216:219], v197 offset:52224
	ds_read_b128 v[220:223], v197 offset:53248
	ds_read_b128 v[224:227], v197 offset:54272
	ds_read_b128 v[238:241], v197 offset:55296
	ds_read_b128 v[242:245], v197 offset:56320
	global_load_lds_dwordx4 v[230:231], off
	s_add_i32 m0, s20, 0x2000
	s_add_u32 s4, s4, 0x40080
	v_lshl_add_u64 v[230:231], v[234:235], 0, s[10:11]
	s_addc_u32 s5, s5, 0
	s_add_i32 s20, s77, s19
	global_load_lds_dwordx4 v[230:231], off
	v_lshl_add_u64 v[230:231], s[4:5], 0, v[144:145]
	s_mov_b32 m0, s20
	s_nop 0
	global_load_lds_dwordx4 v[230:231], off
	v_lshl_add_u64 v[230:231], s[4:5], 0, v[148:149]
	s_add_i32 m0, s20, 0x2000
	s_nop 0
	global_load_lds_dwordx4 v[230:231], off
	v_lshl_add_u64 v[230:231], v[246:247], 0, s[10:11]
	s_mov_b32 m0, s64
	s_nop 0
	global_load_lds_dwordx4 v[230:231], off
	v_lshl_add_u64 v[230:231], v[248:249], 0, s[10:11]
	s_mov_b32 m0, s65
	s_nop 0
	global_load_lds_dwordx4 v[230:231], off
	s_waitcnt vmcnt(8)
	s_waitcnt lgkmcnt(0)
	s_barrier
	s_setprio 1
	s_waitcnt lgkmcnt(0)
	v_mfma_f32_16x16x32_bf16 v[60:63], v[132:135], v[204:207], v[60:63]
	v_mfma_f32_16x16x32_bf16 v[56:59], v[140:143], v[204:207], v[56:59]
	v_mfma_f32_16x16x32_bf16 v[44:47], v[132:135], v[212:215], v[44:47]
	v_mfma_f32_16x16x32_bf16 v[40:43], v[140:143], v[212:215], v[40:43]
	v_mfma_f32_16x16x32_bf16 v[28:31], v[132:135], v[220:223], v[28:31]
	v_mfma_f32_16x16x32_bf16 v[24:27], v[140:143], v[220:223], v[24:27]
	v_mfma_f32_16x16x32_bf16 v[12:15], v[132:135], v[238:241], v[12:15]
	v_mfma_f32_16x16x32_bf16 v[8:11], v[140:143], v[238:241], v[8:11]
	v_mfma_f32_16x16x32_bf16 v[60:63], v[136:139], v[208:211], v[60:63]
	v_mfma_f32_16x16x32_bf16 v[56:59], v[154:157], v[208:211], v[56:59]
	v_mfma_f32_16x16x32_bf16 v[44:47], v[136:139], v[216:219], v[44:47]
	v_mfma_f32_16x16x32_bf16 v[40:43], v[154:157], v[216:219], v[40:43]
	v_mfma_f32_16x16x32_bf16 v[28:31], v[136:139], v[224:227], v[28:31]
	v_mfma_f32_16x16x32_bf16 v[24:27], v[154:157], v[224:227], v[24:27]
	v_mfma_f32_16x16x32_bf16 v[12:15], v[136:139], v[242:245], v[12:15]
	v_mfma_f32_16x16x32_bf16 v[8:11], v[154:157], v[242:245], v[8:11]
	s_setprio 0
	s_setprio 1
	v_mfma_f32_16x16x32_bf16 v[52:55], v[158:161], v[204:207], v[52:55]
	v_mfma_f32_16x16x32_bf16 v[48:51], v[166:169], v[204:207], v[48:51]
	v_mfma_f32_16x16x32_bf16 v[36:39], v[158:161], v[212:215], v[36:39]
	v_mfma_f32_16x16x32_bf16 v[32:35], v[166:169], v[212:215], v[32:35]
	v_mfma_f32_16x16x32_bf16 v[20:23], v[158:161], v[220:223], v[20:23]
	v_mfma_f32_16x16x32_bf16 v[16:19], v[166:169], v[220:223], v[16:19]
	v_mfma_f32_16x16x32_bf16 v[4:7], v[158:161], v[238:241], v[4:7]
	v_mfma_f32_16x16x32_bf16 v[0:3], v[166:169], v[238:241], v[0:3]
	v_mfma_f32_16x16x32_bf16 v[52:55], v[162:165], v[208:211], v[52:55]
	v_mfma_f32_16x16x32_bf16 v[48:51], v[200:203], v[208:211], v[48:51]
	v_mfma_f32_16x16x32_bf16 v[36:39], v[162:165], v[216:219], v[36:39]
	v_mfma_f32_16x16x32_bf16 v[32:35], v[200:203], v[216:219], v[32:35]
	v_mfma_f32_16x16x32_bf16 v[20:23], v[162:165], v[224:227], v[20:23]
	v_mfma_f32_16x16x32_bf16 v[16:19], v[200:203], v[224:227], v[16:19]
	v_mfma_f32_16x16x32_bf16 v[4:7], v[162:165], v[242:245], v[4:7]
	v_mfma_f32_16x16x32_bf16 v[0:3], v[200:203], v[242:245], v[0:3]
	s_setprio 0
	s_barrier
	s_add_i32 s75, s75, 2
	s_add_u32 s0, s0, 0x100
	s_addc_u32 s1, s1, 0
	s_add_u32 s73, s73, 0x100
	s_addc_u32 s74, s74, 0
	s_cmp_gt_u32 s75, 13
	s_cbranch_scc0 .LBB0_224
	s_and_b64 vcc, exec, s[50:51]
	s_cbranch_vccz .LBB0_227
	s_barrier

; #define PG8_STAGE(bufoff, gbase, voff) do { _Pragma("unroll") for (int _i = 0; _i < 2; ++_i) \
;         __builtin_amdgcn_global_load_lds((const unsigned*)((const char*)(gbase) + (voff)[_i]), (PG8_LAS unsigned*)(lds + (bufoff) + ldsw + _i * 8192), 16, 0, 0); } while (0)
; #define PG8_LDA(dst, b, h) do { _Pragma("unroll") for (int m = 0; m < 4; ++m) _Pragma("unroll") for (int k = 0; k < 2; ++k) dst[m][k] = *(const PG8_LAS bf16x8*)(lds + PG8_SA(b, h) + aoff + m * 2048 + k * 1024); } while (0)
; #define PG8_LDB(dst, b, h) do { _Pragma("unroll") for (int n = 0; n < 2; ++n) _Pragma("unroll") for (int k = 0; k < 2; ++k) dst[n][k] = *(const PG8_LAS bf16x8*)(lds + PG8_SB(b, h) + boff + n * 2048 + k * 1024); } while (0)
; #define PG8_WAIT_V(n) asm volatile("s_waitcnt vmcnt(" #n ")" ::: "memory")
; #define PG8_WAIT_L(n) asm volatile("s_waitcnt lgkmcnt(" #n ")" ::: "memory")
; #define PG8_BAR __builtin_amdgcn_s_barrier()
; #define PG8_SCHED __builtin_amdgcn_sched_barrier(0)
; template <class Epi, class Sched, bool ALIGN_EPI = false, bool SP2 = false>
; __device__ __forceinline__ void gemm_phase(PG8_LAS unsigned char* lds, const Gemm g, const Sched& S, const Epi& E, const int tid_in) {
;     ...
;         const char* nA = has_next ? (const char*)g.A + (size_t)nxt.pm * tstepA + (size_t)(nxt.pm >> 3) * g.abx : cA; const char* nB = has_next ? (const char*)g.Bt + (size_t)nxt.pn * tstepB : cB;
;         for (int t = 0; t < nt; t += 2) {
;             const bool last = (t == nt - 2);
;             const char* a1 = cA + (size_t)(t + 1) * kstep;
;             const char* a2 = last ? nA : cA + (size_t)(t + 2) * kstep; const char* b2 = last ? nB : cB + (size_t)(t + 2) * kstep;
;             const char* a3 = a2 + kstep; const char* b3 = b2 + kstep;
;             if (last && has_next) S.a_ready(nxt);
;             if constexpr (SP2) {
;             PG8_LDB(B0, 0, 0); PG8_LDB(B1, 0, 1); PG8_SCHED; PG8_LDA(At, 0, 0); PG8_STAGE(PG8_SA(1, 1), a1 + hstepA, voffA);
;             PG8_WAIT_V(8); PG8_WAIT_L(0); PG8_BAR; PG8_MMA(0, 0, At, B0); PG8_MMA(0, 1, At, B1); PG8_BAR; PG8_SCHED;
;     ...
;         for (int a = 0; a < 2; ++a)
; #pragma unroll
;             for (int b = 0; b < 2; ++b)
; #pragma unroll
;                 for (int m = 0; m < 4; ++m)
; #pragma unroll
;                     for (int n = 0; n < 2; ++n) acc[a][b][m][n] = (f32x4){0.f, 0.f, 0.f, 0.f};
.LBB0_612:
	s_ashr_i32 s53, s52, 31
	s_lshl_b64 s[4:5], s[52:53], 19
	s_add_u32 s54, s22, s4
	s_addc_u32 s55, s23, s5
	s_and_b64 s[4:5], s[40:41], exec
	s_cselect_b32 s53, s55, s1
	s_cselect_b32 s61, s54, s0
	s_ashr_i32 s51, s50, 31
	s_lshl_b64 s[4:5], s[50:51], 19
	s_add_u32 s56, s24, s4
	s_addc_u32 s57, s25, s5
	s_and_b64 s[4:5], s[40:41], exec
	s_cselect_b32 s51, s57, s21
	s_cselect_b32 s62, s56, s20
	s_add_u32 s0, s0, 0x40080
	s_addc_u32 s1, s1, 0
	s_add_u32 s63, s20, 0x100
	v_mov_b32_e32 v0, 0
	s_addc_u32 s64, s21, 0
	s_mov_b32 s65, -2
	s_cmp_gt_u32 s14, 1
	s_cselect_b32 s101, 1, 0
	v_mov_b32_e32 v1, v0
	v_mov_b32_e32 v2, v0
	v_mov_b32_e32 v3, v0
	v_mov_b32_e32 v4, v0
	v_mov_b32_e32 v5, v0
	v_mov_b32_e32 v6, v0
	v_mov_b32_e32 v7, v0
	v_mov_b32_e32 v16, v0
	v_mov_b32_e32 v17, v0
	v_mov_b32_e32 v18, v0
	v_mov_b32_e32 v19, v0
	v_mov_b32_e32 v20, v0
	v_mov_b32_e32 v21, v0
	v_mov_b32_e32 v22, v0
	v_mov_b32_e32 v23, v0
	v_mov_b32_e32 v32, v0
	v_mov_b32_e32 v33, v0
	v_mov_b32_e32 v34, v0
	v_mov_b32_e32 v35, v0
	v_mov_b32_e32 v36, v0
	v_mov_b32_e32 v37, v0
	v_mov_b32_e32 v38, v0
	v_mov_b32_e32 v39, v0
	v_mov_b32_e32 v48, v0
	v_mov_b32_e32 v49, v0
	v_mov_b32_e32 v50, v0
	v_mov_b32_e32 v51, v0
	v_mov_b32_e32 v52, v0
	v_mov_b32_e32 v53, v0
	v_mov_b32_e32 v54, v0
	v_mov_b32_e32 v55, v0
	v_mov_b32_e32 v8, v0
	v_mov_b32_e32 v9, v0
	v_mov_b32_e32 v10, v0
	v_mov_b32_e32 v11, v0
	v_mov_b32_e32 v12, v0
	v_mov_b32_e32 v13, v0
	v_mov_b32_e32 v14, v0
	v_mov_b32_e32 v15, v0
	v_mov_b32_e32 v24, v0
	v_mov_b32_e32 v25, v0
	v_mov_b32_e32 v26, v0
	v_mov_b32_e32 v27, v0
	v_mov_b32_e32 v28, v0
	v_mov_b32_e32 v29, v0
	v_mov_b32_e32 v30, v0
	v_mov_b32_e32 v31, v0
	v_mov_b32_e32 v40, v0
	v_mov_b32_e32 v41, v0
	v_mov_b32_e32 v42, v0
	v_mov_b32_e32 v43, v0
	v_mov_b32_e32 v44, v0
	v_mov_b32_e32 v45, v0
	v_mov_b32_e32 v46, v0
	v_mov_b32_e32 v47, v0
	v_mov_b32_e32 v56, v0
	v_mov_b32_e32 v57, v0
	v_mov_b32_e32 v58, v0
	v_mov_b32_e32 v59, v0
	v_mov_b32_e32 v60, v0
	v_mov_b32_e32 v61, v0
	v_mov_b32_e32 v62, v0
	v_mov_b32_e32 v63, v0
	v_mov_b32_e32 v64, v0
	v_mov_b32_e32 v65, v0
	v_mov_b32_e32 v66, v0
	v_mov_b32_e32 v67, v0
	v_mov_b32_e32 v68, v0
	v_mov_b32_e32 v69, v0
	v_mov_b32_e32 v70, v0
	v_mov_b32_e32 v71, v0
	v_mov_b32_e32 v80, v0
	v_mov_b32_e32 v81, v0
	v_mov_b32_e32 v82, v0
	v_mov_b32_e32 v83, v0
	v_mov_b32_e32 v84, v0
	v_mov_b32_e32 v85, v0
	v_mov_b32_e32 v86, v0
	v_mov_b32_e32 v87, v0
	v_mov_b32_e32 v96, v0
	v_mov_b32_e32 v97, v0
	v_mov_b32_e32 v98, v0
	v_mov_b32_e32 v99, v0
	v_mov_b32_e32 v100, v0
	v_mov_b32_e32 v101, v0
	v_mov_b32_e32 v102, v0
	v_mov_b32_e32 v103, v0
	v_mov_b32_e32 v116, v0
	v_mov_b32_e32 v117, v0
	v_mov_b32_e32 v118, v0
	v_mov_b32_e32 v119, v0
	v_mov_b32_e32 v120, v0
	v_mov_b32_e32 v121, v0
	v_mov_b32_e32 v122, v0
	v_mov_b32_e32 v123, v0
	v_mov_b32_e32 v72, v0
	v_mov_b32_e32 v73, v0
	v_mov_b32_e32 v74, v0
	v_mov_b32_e32 v75, v0
	v_mov_b32_e32 v76, v0
	v_mov_b32_e32 v77, v0
	v_mov_b32_e32 v78, v0
	v_mov_b32_e32 v79, v0
	v_mov_b32_e32 v88, v0
	v_mov_b32_e32 v89, v0
	v_mov_b32_e32 v90, v0
	v_mov_b32_e32 v91, v0
	v_mov_b32_e32 v92, v0
	v_mov_b32_e32 v93, v0
	v_mov_b32_e32 v94, v0
	v_mov_b32_e32 v95, v0
	v_mov_b32_e32 v104, v0
	v_mov_b32_e32 v105, v0
	v_mov_b32_e32 v106, v0
	v_mov_b32_e32 v107, v0
	v_mov_b32_e32 v108, v0
	v_mov_b32_e32 v109, v0
	v_mov_b32_e32 v110, v0
	v_mov_b32_e32 v111, v0
	v_mov_b32_e32 v124, v0
	v_mov_b32_e32 v125, v0
	v_mov_b32_e32 v126, v0
	v_mov_b32_e32 v127, v0
	v_mov_b32_e32 v128, v0
	v_mov_b32_e32 v129, v0
	v_mov_b32_e32 v130, v0
	v_mov_b32_e32 v131, v0
.LBB0_613:
	s_add_u32 s4, s0, 0xfffc0080
	s_addc_u32 s5, s1, -1
	s_add_i32 s66, 0, 0x10000
	s_cmp_eq_u32 s65, 12
	s_cselect_b32 s21, s53, s5
	s_cselect_b32 s20, s61, s4
	s_cselect_b32 s5, s51, s64
	s_cselect_b32 s4, s62, s63
	s_add_i32 s70, 0, 0x14000
	v_add_u32_e32 v144, s66, v176
	v_add_u32_e32 v168, s70, v176
	ds_read_b128 v[132:135], v144
	ds_read_b128 v[136:139], v144 offset:1024
	ds_read_b128 v[140:143], v144 offset:2048
	ds_read_b128 v[144:147], v144 offset:3072
	ds_read_b128 v[148:151], v168
	ds_read_b128 v[152:155], v168 offset:1024
	ds_read_b128 v[164:167], v168 offset:2048
	ds_read_b128 v[168:171], v168 offset:3072
	v_lshl_add_u64 v[174:175], s[0:1], 0, v[160:161]
	s_add_i32 m0, s26, 0xc000
	ds_read_b128 v[180:183], v179
	ds_read_b128 v[184:187], v179 offset:1024
	ds_read_b128 v[188:191], v179 offset:2048
	ds_read_b128 v[192:195], v179 offset:3072
	ds_read_b128 v[196:199], v179 offset:4096
	ds_read_b128 v[204:207], v179 offset:5120
	ds_read_b128 v[208:211], v179 offset:6144
	ds_read_b128 v[212:215], v179 offset:7168
	global_load_lds_dwordx4 v[174:175], off
	v_lshl_add_u64 v[174:175], s[0:1], 0, v[162:163]
	s_add_i32 m0, s26, 0xe000
	s_nop 0
	global_load_lds_dwordx4 v[174:175], off
	s_cmp_lg_u32 s101, 0
	s_cbranch_scc1 .Lmy_rw_gin_0r
	s_waitcnt vmcnt(8)
	s_branch .Lmy_rw_gin_0j

; #define PG8_STAGE(bufoff, gbase, voff) do { _Pragma("unroll") for (int _i = 0; _i < 2; ++_i) \
;         __builtin_amdgcn_global_load_lds((const unsigned*)((const char*)(gbase) + (voff)[_i]), (PG8_LAS unsigned*)(lds + (bufoff) + ldsw + _i * 8192), 16, 0, 0); } while (0)
; #define PG8_LDA(dst, b, h) do { _Pragma("unroll") for (int m = 0; m < 4; ++m) _Pragma("unroll") for (int k = 0; k < 2; ++k) dst[m][k] = *(const PG8_LAS bf16x8*)(lds + PG8_SA(b, h) + aoff + m * 2048 + k * 1024); } while (0)
; #define PG8_MMA(ai, bj, At, Bt) do { __builtin_amdgcn_s_setprio(1); _Pragma("unroll") for (int m = 0; m < 4; ++m) _Pragma("unroll") for (int n = 0; n < 2; ++n) _Pragma("unroll") for (int k = 0; k < 2; ++k) \
;         acc[ai][bj][m][n] = __builtin_amdgcn_mfma_f32_16x16x32_bf16(Bt[n][k], At[m][k], acc[ai][bj][m][n], 0, 0, 0); __builtin_amdgcn_s_setprio(0); } while (0)
; #define PG8_WAIT_V(n) asm volatile("s_waitcnt vmcnt(" #n ")" ::: "memory")
; #define PG8_WAIT_L(n) asm volatile("s_waitcnt lgkmcnt(" #n ")" ::: "memory")
; #define PG8_BAR __builtin_amdgcn_s_barrier()
; #define PG8_SCHED __builtin_amdgcn_sched_barrier(0)
; template <class Epi, class Sched, bool ALIGN_EPI = false, bool SP2 = false>
; __device__ __forceinline__ void gemm_phase(PG8_LAS unsigned char* lds, const Gemm g, const Sched& S, const Epi& E, const int tid_in) {
;     ...
;             PG8_WAIT_V(8); PG8_WAIT_L(0); PG8_BAR; PG8_MMA(0, 0, At, B0); PG8_MMA(0, 1, At, B1); PG8_BAR; PG8_SCHED;
;             PG8_LDA(At, 0, 1); PG8_STAGE(PG8_SB(0, 0), b2, voffB); PG8_STAGE(PG8_SB(0, 1), b2 + hstepB, voffB); PG8_STAGE(PG8_SA(0, 0), a2, voffA);
;             PG8_WAIT_V(8); PG8_WAIT_L(0); PG8_BAR; PG8_MMA(1, 0, At, B0); PG8_MMA(1, 1, At, B1); PG8_BAR; PG8_SCHED;
.Lmy_rw_gin_0j:
	s_waitcnt lgkmcnt(0)
	s_barrier
	s_setprio 1
	s_waitcnt lgkmcnt(0)
	v_mfma_f32_16x16x32_bf16 v[128:131], v[132:135], v[180:183], v[128:131]
	v_mfma_f32_16x16x32_bf16 v[124:127], v[140:143], v[180:183], v[124:127]
	v_mfma_f32_16x16x32_bf16 v[108:111], v[132:135], v[188:191], v[108:111]
	v_mfma_f32_16x16x32_bf16 v[104:107], v[140:143], v[188:191], v[104:107]
	v_mfma_f32_16x16x32_bf16 v[92:95], v[132:135], v[196:199], v[92:95]
	v_mfma_f32_16x16x32_bf16 v[88:91], v[140:143], v[196:199], v[88:91]
	v_mfma_f32_16x16x32_bf16 v[76:79], v[132:135], v[208:211], v[76:79]
	v_mfma_f32_16x16x32_bf16 v[72:75], v[140:143], v[208:211], v[72:75]
	v_mfma_f32_16x16x32_bf16 v[128:131], v[136:139], v[184:187], v[128:131]
	v_mfma_f32_16x16x32_bf16 v[124:127], v[144:147], v[184:187], v[124:127]
	v_mfma_f32_16x16x32_bf16 v[108:111], v[136:139], v[192:195], v[108:111]
	v_mfma_f32_16x16x32_bf16 v[104:107], v[144:147], v[192:195], v[104:107]
	v_mfma_f32_16x16x32_bf16 v[92:95], v[136:139], v[204:207], v[92:95]
	v_mfma_f32_16x16x32_bf16 v[88:91], v[144:147], v[204:207], v[88:91]
	v_mfma_f32_16x16x32_bf16 v[76:79], v[136:139], v[212:215], v[76:79]
	v_mfma_f32_16x16x32_bf16 v[72:75], v[144:147], v[212:215], v[72:75]
	s_setprio 0
	s_setprio 1
	v_mfma_f32_16x16x32_bf16 v[120:123], v[148:151], v[180:183], v[120:123]
	v_mfma_f32_16x16x32_bf16 v[116:119], v[164:167], v[180:183], v[116:119]
	v_mfma_f32_16x16x32_bf16 v[100:103], v[148:151], v[188:191], v[100:103]
	v_mfma_f32_16x16x32_bf16 v[96:99], v[164:167], v[188:191], v[96:99]
	v_mfma_f32_16x16x32_bf16 v[84:87], v[148:151], v[196:199], v[84:87]
	v_mfma_f32_16x16x32_bf16 v[80:83], v[164:167], v[196:199], v[80:83]
	v_mfma_f32_16x16x32_bf16 v[68:71], v[148:151], v[208:211], v[68:71]
	v_mfma_f32_16x16x32_bf16 v[64:67], v[164:167], v[208:211], v[64:67]
	v_mfma_f32_16x16x32_bf16 v[120:123], v[152:155], v[184:187], v[120:123]
	v_mfma_f32_16x16x32_bf16 v[116:119], v[168:171], v[184:187], v[116:119]
	v_mfma_f32_16x16x32_bf16 v[100:103], v[152:155], v[192:195], v[100:103]
	v_mfma_f32_16x16x32_bf16 v[96:99], v[168:171], v[192:195], v[96:99]
	v_mfma_f32_16x16x32_bf16 v[84:87], v[152:155], v[204:207], v[84:87]
	v_mfma_f32_16x16x32_bf16 v[80:83], v[168:171], v[204:207], v[80:83]
	v_mfma_f32_16x16x32_bf16 v[68:71], v[152:155], v[212:215], v[68:71]
	v_mfma_f32_16x16x32_bf16 v[64:67], v[168:171], v[212:215], v[64:67]
	s_setprio 0
	s_barrier
	s_add_i32 s66, s66, s13
	v_lshl_add_u64 v[174:175], s[4:5], 0, v[114:115]
	s_mov_b32 m0, s66
	ds_read_b128 v[180:183], v179 offset:16384
	ds_read_b128 v[184:187], v179 offset:17408
	ds_read_b128 v[188:191], v179 offset:18432
	ds_read_b128 v[192:195], v179 offset:19456
	ds_read_b128 v[196:199], v179 offset:20480
	ds_read_b128 v[204:207], v179 offset:21504
	ds_read_b128 v[208:211], v179 offset:22528
	ds_read_b128 v[212:215], v179 offset:23552
	global_load_lds_dwordx4 v[174:175], off
	s_add_i32 m0, s66, 0x2000
	s_add_u32 s66, s4, 0x40000
	v_lshl_add_u64 v[200:201], s[4:5], 0, v[158:159]
	s_addc_u32 s67, s5, 0
	s_add_i32 s70, s70, s13
	global_load_lds_dwordx4 v[200:201], off
	v_lshl_add_u64 v[202:203], s[66:67], 0, v[114:115]
	s_mov_b32 m0, s70
	v_lshl_add_u64 v[216:217], s[20:21], 0, v[156:157]
	global_load_lds_dwordx4 v[202:203], off
	v_lshl_add_u64 v[202:203], s[66:67], 0, v[158:159]
	s_add_i32 m0, s70, 0x2000
	s_nop 0
	global_load_lds_dwordx4 v[202:203], off
	v_lshl_add_u64 v[202:203], s[20:21], 0, v[112:113]
	s_mov_b32 m0, s26
	s_nop 0
	global_load_lds_dwordx4 v[202:203], off
	s_mov_b32 m0, s27
	s_nop 0
	global_load_lds_dwordx4 v[216:217], off
	s_cmp_lg_u32 s101, 0
	s_cbranch_scc1 .Lmy_rw_gin_1r
	s_waitcnt vmcnt(8)
	s_branch .Lmy_rw_gin_1j

; #define PG8_STAGE(bufoff, gbase, voff) do { _Pragma("unroll") for (int _i = 0; _i < 2; ++_i) \
;         __builtin_amdgcn_global_load_lds((const unsigned*)((const char*)(gbase) + (voff)[_i]), (PG8_LAS unsigned*)(lds + (bufoff) + ldsw + _i * 8192), 16, 0, 0); } while (0)
; #define PG8_LDA(dst, b, h) do { _Pragma("unroll") for (int m = 0; m < 4; ++m) _Pragma("unroll") for (int k = 0; k < 2; ++k) dst[m][k] = *(const PG8_LAS bf16x8*)(lds + PG8_SA(b, h) + aoff + m * 2048 + k * 1024); } while (0)
; #define PG8_LDB(dst, b, h) do { _Pragma("unroll") for (int n = 0; n < 2; ++n) _Pragma("unroll") for (int k = 0; k < 2; ++k) dst[n][k] = *(const PG8_LAS bf16x8*)(lds + PG8_SB(b, h) + boff + n * 2048 + k * 1024); } while (0)
; #define PG8_MMA(ai, bj, At, Bt) do { __builtin_amdgcn_s_setprio(1); _Pragma("unroll") for (int m = 0; m < 4; ++m) _Pragma("unroll") for (int n = 0; n < 2; ++n) _Pragma("unroll") for (int k = 0; k < 2; ++k) \
;         acc[ai][bj][m][n] = __builtin_amdgcn_mfma_f32_16x16x32_bf16(Bt[n][k], At[m][k], acc[ai][bj][m][n], 0, 0, 0); __builtin_amdgcn_s_setprio(0); } while (0)
; #define PG8_WAIT_V(n) asm volatile("s_waitcnt vmcnt(" #n ")" ::: "memory")
; #define PG8_WAIT_L(n) asm volatile("s_waitcnt lgkmcnt(" #n ")" ::: "memory")
; #define PG8_BAR __builtin_amdgcn_s_barrier()
; #define PG8_SCHED __builtin_amdgcn_sched_barrier(0)
; template <class Epi, class Sched, bool ALIGN_EPI = false, bool SP2 = false>
; __device__ __forceinline__ void gemm_phase(PG8_LAS unsigned char* lds, const Gemm g, const Sched& S, const Epi& E, const int tid_in) {
;     ...
;             PG8_WAIT_V(8); PG8_WAIT_L(0); PG8_BAR; PG8_MMA(1, 0, At, B0); PG8_MMA(1, 1, At, B1); PG8_BAR; PG8_SCHED;
;             PG8_LDB(B0, 1, 0); PG8_LDB(B1, 1, 1); PG8_SCHED; PG8_LDA(At, 1, 0); PG8_STAGE(PG8_SA(0, 1), a2 + hstepA, voffA);
;             PG8_WAIT_V(8); PG8_WAIT_L(0); PG8_BAR; PG8_MMA(0, 0, At, B0); PG8_MMA(0, 1, At, B1); PG8_BAR; PG8_SCHED;
.Lmy_rw_gin_1j:
	s_mov_b32 s101, 0
	s_waitcnt lgkmcnt(0)
	s_barrier
	s_setprio 1
	s_waitcnt lgkmcnt(0)
	v_mfma_f32_16x16x32_bf16 v[60:63], v[132:135], v[180:183], v[60:63]
	v_mfma_f32_16x16x32_bf16 v[56:59], v[140:143], v[180:183], v[56:59]
	v_mfma_f32_16x16x32_bf16 v[44:47], v[132:135], v[188:191], v[44:47]
	v_mfma_f32_16x16x32_bf16 v[40:43], v[140:143], v[188:191], v[40:43]
	v_mfma_f32_16x16x32_bf16 v[28:31], v[132:135], v[196:199], v[28:31]
	v_mfma_f32_16x16x32_bf16 v[24:27], v[140:143], v[196:199], v[24:27]
	v_mfma_f32_16x16x32_bf16 v[12:15], v[132:135], v[208:211], v[12:15]
	v_mfma_f32_16x16x32_bf16 v[8:11], v[140:143], v[208:211], v[8:11]
	v_mfma_f32_16x16x32_bf16 v[60:63], v[136:139], v[184:187], v[60:63]
	v_mfma_f32_16x16x32_bf16 v[56:59], v[144:147], v[184:187], v[56:59]
	v_mfma_f32_16x16x32_bf16 v[44:47], v[136:139], v[192:195], v[44:47]
	v_mfma_f32_16x16x32_bf16 v[40:43], v[144:147], v[192:195], v[40:43]
	v_mfma_f32_16x16x32_bf16 v[28:31], v[136:139], v[204:207], v[28:31]
	v_mfma_f32_16x16x32_bf16 v[24:27], v[144:147], v[204:207], v[24:27]
	v_mfma_f32_16x16x32_bf16 v[12:15], v[136:139], v[212:215], v[12:15]
	v_mfma_f32_16x16x32_bf16 v[8:11], v[144:147], v[212:215], v[8:11]
	s_setprio 0
	s_setprio 1
	v_mfma_f32_16x16x32_bf16 v[52:55], v[148:151], v[180:183], v[52:55]
	v_mfma_f32_16x16x32_bf16 v[48:51], v[164:167], v[180:183], v[48:51]
	v_mfma_f32_16x16x32_bf16 v[36:39], v[148:151], v[188:191], v[36:39]
	v_mfma_f32_16x16x32_bf16 v[32:35], v[164:167], v[188:191], v[32:35]
	v_mfma_f32_16x16x32_bf16 v[20:23], v[148:151], v[196:199], v[20:23]
	v_mfma_f32_16x16x32_bf16 v[16:19], v[164:167], v[196:199], v[16:19]
	v_mfma_f32_16x16x32_bf16 v[4:7], v[148:151], v[208:211], v[4:7]
	v_mfma_f32_16x16x32_bf16 v[0:3], v[164:167], v[208:211], v[0:3]
	v_mfma_f32_16x16x32_bf16 v[52:55], v[152:155], v[184:187], v[52:55]
	v_mfma_f32_16x16x32_bf16 v[48:51], v[168:171], v[184:187], v[48:51]
	v_mfma_f32_16x16x32_bf16 v[36:39], v[152:155], v[192:195], v[36:39]
	v_mfma_f32_16x16x32_bf16 v[32:35], v[168:171], v[192:195], v[32:35]
	v_mfma_f32_16x16x32_bf16 v[20:23], v[152:155], v[204:207], v[20:23]
	v_mfma_f32_16x16x32_bf16 v[16:19], v[168:171], v[204:207], v[16:19]
	v_mfma_f32_16x16x32_bf16 v[4:7], v[152:155], v[212:215], v[4:7]
	v_mfma_f32_16x16x32_bf16 v[0:3], v[168:171], v[212:215], v[0:3]
	s_setprio 0
	s_barrier
	s_add_i32 s66, 0, 0x18000
	s_add_i32 s67, 0, 0x1c000
	v_add_u32_e32 v144, s66, v176
	v_add_u32_e32 v168, s67, v176
	ds_read_b128 v[132:135], v144
	ds_read_b128 v[136:139], v144 offset:1024
	ds_read_b128 v[140:143], v144 offset:2048
	ds_read_b128 v[144:147], v144 offset:3072
	ds_read_b128 v[148:151], v168
	ds_read_b128 v[152:155], v168 offset:1024
	ds_read_b128 v[164:167], v168 offset:2048
	ds_read_b128 v[168:171], v168 offset:3072
	s_add_u32 s20, s20, 0x40000
	s_addc_u32 s21, s21, 0
	s_mov_b32 m0, s28
	v_lshl_add_u64 v[218:219], s[20:21], 0, v[112:113]
	ds_read_b128 v[180:183], v179 offset:32768
	ds_read_b128 v[184:187], v179 offset:33792
	ds_read_b128 v[188:191], v179 offset:34816
	ds_read_b128 v[192:195], v179 offset:35840
	ds_read_b128 v[196:199], v179 offset:36864
	ds_read_b128 v[204:207], v179 offset:37888
	ds_read_b128 v[208:211], v179 offset:38912
	ds_read_b128 v[212:215], v179 offset:39936
	global_load_lds_dwordx4 v[218:219], off
	v_lshl_add_u64 v[218:219], s[20:21], 0, v[156:157]
	s_mov_b32 m0, s29
	s_nop 0
	global_load_lds_dwordx4 v[218:219], off
	s_waitcnt vmcnt(8)
	s_waitcnt lgkmcnt(0)
	s_barrier
	s_setprio 1
	s_waitcnt lgkmcnt(0)
	v_mfma_f32_16x16x32_bf16 v[128:131], v[132:135], v[180:183], v[128:131]
	v_mfma_f32_16x16x32_bf16 v[124:127], v[140:143], v[180:183], v[124:127]
	v_mfma_f32_16x16x32_bf16 v[108:111], v[132:135], v[188:191], v[108:111]
	v_mfma_f32_16x16x32_bf16 v[104:107], v[140:143], v[188:191], v[104:107]
	v_mfma_f32_16x16x32_bf16 v[92:95], v[132:135], v[196:199], v[92:95]
	v_mfma_f32_16x16x32_bf16 v[88:91], v[140:143], v[196:199], v[88:91]
	v_mfma_f32_16x16x32_bf16 v[76:79], v[132:135], v[208:211], v[76:79]
	v_mfma_f32_16x16x32_bf16 v[72:75], v[140:143], v[208:211], v[72:75]
	v_mfma_f32_16x16x32_bf16 v[128:131], v[136:139], v[184:187], v[128:131]
	v_mfma_f32_16x16x32_bf16 v[124:127], v[144:147], v[184:187], v[124:127]
	v_mfma_f32_16x16x32_bf16 v[108:111], v[136:139], v[192:195], v[108:111]
	v_mfma_f32_16x16x32_bf16 v[104:107], v[144:147], v[192:195], v[104:107]
	v_mfma_f32_16x16x32_bf16 v[92:95], v[136:139], v[204:207], v[92:95]
	v_mfma_f32_16x16x32_bf16 v[88:91], v[144:147], v[204:207], v[88:91]
	v_mfma_f32_16x16x32_bf16 v[76:79], v[136:139], v[212:215], v[76:79]
	v_mfma_f32_16x16x32_bf16 v[72:75], v[144:147], v[212:215], v[72:75]
	s_setprio 0
	s_setprio 1
	v_mfma_f32_16x16x32_bf16 v[120:123], v[148:151], v[180:183], v[120:123]
	v_mfma_f32_16x16x32_bf16 v[116:119], v[164:167], v[180:183], v[116:119]
	v_mfma_f32_16x16x32_bf16 v[100:103], v[148:151], v[188:191], v[100:103]
	v_mfma_f32_16x16x32_bf16 v[96:99], v[164:167], v[188:191], v[96:99]
	v_mfma_f32_16x16x32_bf16 v[84:87], v[148:151], v[196:199], v[84:87]
	v_mfma_f32_16x16x32_bf16 v[80:83], v[164:167], v[196:199], v[80:83]
	v_mfma_f32_16x16x32_bf16 v[68:71], v[148:151], v[208:211], v[68:71]
	v_mfma_f32_16x16x32_bf16 v[64:67], v[164:167], v[208:211], v[64:67]
	v_mfma_f32_16x16x32_bf16 v[120:123], v[152:155], v[184:187], v[120:123]
	v_mfma_f32_16x16x32_bf16 v[116:119], v[168:171], v[184:187], v[116:119]
	v_mfma_f32_16x16x32_bf16 v[100:103], v[152:155], v[192:195], v[100:103]
	v_mfma_f32_16x16x32_bf16 v[96:99], v[168:171], v[192:195], v[96:99]
	v_mfma_f32_16x16x32_bf16 v[84:87], v[152:155], v[204:207], v[84:87]
	v_mfma_f32_16x16x32_bf16 v[80:83], v[168:171], v[204:207], v[80:83]
	v_mfma_f32_16x16x32_bf16 v[68:71], v[152:155], v[212:215], v[68:71]
	v_mfma_f32_16x16x32_bf16 v[64:67], v[168:171], v[212:215], v[64:67]
	s_setprio 0
	s_barrier
; #define PG8_STAGE(bufoff, gbase, voff) do { _Pragma("unroll") for (int _i = 0; _i < 2; ++_i) \
;         __builtin_amdgcn_global_load_lds((const unsigned*)((const char*)(gbase) + (voff)[_i]), (PG8_LAS unsigned*)(lds + (bufoff) + ldsw + _i * 8192), 16, 0, 0); } while (0)
; #define PG8_LDA(dst, b, h) do { _Pragma("unroll") for (int m = 0; m < 4; ++m) _Pragma("unroll") for (int k = 0; k < 2; ++k) dst[m][k] = *(const PG8_LAS bf16x8*)(lds + PG8_SA(b, h) + aoff + m * 2048 + k * 1024); } while (0)
; #define PG8_BAR __builtin_amdgcn_s_barrier()
; template <class Epi, class Sched, bool ALIGN_EPI = false, bool SP2 = false>
; __device__ __forceinline__ void gemm_phase(PG8_LAS unsigned char* lds, const Gemm g, const Sched& S, const Epi& E, const int tid_in) {
;     ...
;             PG8_LDA(At, 1, 1); PG8_STAGE(PG8_SB(1, 0), b3, voffB); PG8_STAGE(PG8_SB(1, 1), b3 + hstepB, voffB); PG8_STAGE(PG8_SA(1, 0), a3, voffA);
;             PG8_WAIT_V(8); PG8_WAIT_L(0); PG8_BAR; PG8_MMA(1, 0, At, B0); PG8_MMA(1, 1, At, B1); PG8_BAR; PG8_SCHED;
;             } else {
;             PG8_LDB(B0, 0, 0); PG8_SCHED; PG8_LDA(At, 0, 0); PG8_STAGE(PG8_SA(1, 1), a1 + hstepA, voffA);
;             PG8_WAIT_L(8); PG8_BAR; PG8_WAIT_L(0); PG8_MMA(0, 0, At, B0); PG8_BAR; PG8_SCHED;
;             PG8_LDB(B1, 0, 1); PG8_STAGE(PG8_SB(0, 0), b2, voffB);
;             PG8_BAR; PG8_WAIT_L(0); PG8_MMA(0, 1, At, B1); PG8_BAR;
;             PG8_LDA(At, 0, 1); PG8_STAGE(PG8_SA(0, 0), a2, voffA);
;             PG8_BAR; PG8_WAIT_L(0); PG8_MMA(1, 0, At, B0); PG8_BAR; PG8_SCHED;
;             PG8_STAGE(PG8_SB(0, 1), b2 + hstepB, voffB);
;             PG8_WAIT_V(6); PG8_BAR; PG8_MMA(1, 1, At, B1); PG8_BAR;
;             PG8_LDB(B0, 1, 0); PG8_SCHED; PG8_LDA(At, 1, 0); PG8_STAGE(PG8_SA(0, 1), a2 + hstepA, voffA);
;             PG8_WAIT_L(8); PG8_BAR; PG8_WAIT_L(0); PG8_MMA(0, 0, At, B0); PG8_BAR; PG8_SCHED;
;             PG8_LDB(B1, 1, 1); PG8_STAGE(PG8_SB(1, 0), b3, voffB);
;             PG8_BAR; PG8_WAIT_L(0); PG8_MMA(0, 1, At, B1); PG8_BAR;
;             PG8_LDA(At, 1, 1); PG8_STAGE(PG8_SA(1, 0), a3, voffA);
;             PG8_BAR; PG8_WAIT_L(0); PG8_MMA(1, 0, At, B0); PG8_BAR; PG8_SCHED;
;             PG8_STAGE(PG8_SB(1, 1), b3 + hstepB, voffB);
;             PG8_WAIT_V(6); PG8_BAR; PG8_MMA(1, 1, At, B1); PG8_BAR;
;             }
;         }
;         if constexpr (ALIGN_EPI) { if (wr == 0) PG8_BAR; }
	s_add_i32 s20, s66, s13
	v_lshl_add_u64 v[174:175], v[174:175], 0, s[10:11]
	s_mov_b32 m0, s20
	ds_read_b128 v[180:183], v179 offset:49152
	ds_read_b128 v[184:187], v179 offset:50176
	ds_read_b128 v[188:191], v179 offset:51200
	ds_read_b128 v[192:195], v179 offset:52224
	ds_read_b128 v[196:199], v179 offset:53248
	ds_read_b128 v[204:207], v179 offset:54272
	ds_read_b128 v[208:211], v179 offset:55296
	ds_read_b128 v[212:215], v179 offset:56320
	global_load_lds_dwordx4 v[174:175], off
	s_add_i32 m0, s20, 0x2000
	s_add_u32 s4, s4, 0x40080
	v_lshl_add_u64 v[174:175], v[200:201], 0, s[10:11]
	s_addc_u32 s5, s5, 0
	s_add_i32 s20, s67, s13
	global_load_lds_dwordx4 v[174:175], off
	v_lshl_add_u64 v[174:175], s[4:5], 0, v[114:115]
	s_mov_b32 m0, s20
	s_nop 0
	global_load_lds_dwordx4 v[174:175], off
	v_lshl_add_u64 v[174:175], s[4:5], 0, v[158:159]
	s_add_i32 m0, s20, 0x2000
	s_nop 0
	global_load_lds_dwordx4 v[174:175], off
	v_lshl_add_u64 v[174:175], v[202:203], 0, s[10:11]
	s_mov_b32 m0, s58
	s_nop 0
	global_load_lds_dwordx4 v[174:175], off
	v_lshl_add_u64 v[174:175], v[216:217], 0, s[10:11]
	s_mov_b32 m0, s59
	s_nop 0
	global_load_lds_dwordx4 v[174:175], off
	s_waitcnt vmcnt(8)
	s_waitcnt lgkmcnt(0)
	s_barrier
	s_setprio 1
	s_waitcnt lgkmcnt(0)
	v_mfma_f32_16x16x32_bf16 v[60:63], v[132:135], v[180:183], v[60:63]
	v_mfma_f32_16x16x32_bf16 v[56:59], v[140:143], v[180:183], v[56:59]
	v_mfma_f32_16x16x32_bf16 v[44:47], v[132:135], v[188:191], v[44:47]
	v_mfma_f32_16x16x32_bf16 v[40:43], v[140:143], v[188:191], v[40:43]
	v_mfma_f32_16x16x32_bf16 v[28:31], v[132:135], v[196:199], v[28:31]
	v_mfma_f32_16x16x32_bf16 v[24:27], v[140:143], v[196:199], v[24:27]
	v_mfma_f32_16x16x32_bf16 v[12:15], v[132:135], v[208:211], v[12:15]
	v_mfma_f32_16x16x32_bf16 v[8:11], v[140:143], v[208:211], v[8:11]
	v_mfma_f32_16x16x32_bf16 v[60:63], v[136:139], v[184:187], v[60:63]
	v_mfma_f32_16x16x32_bf16 v[56:59], v[144:147], v[184:187], v[56:59]
	v_mfma_f32_16x16x32_bf16 v[44:47], v[136:139], v[192:195], v[44:47]
	v_mfma_f32_16x16x32_bf16 v[40:43], v[144:147], v[192:195], v[40:43]
	v_mfma_f32_16x16x32_bf16 v[28:31], v[136:139], v[204:207], v[28:31]
	v_mfma_f32_16x16x32_bf16 v[24:27], v[144:147], v[204:207], v[24:27]
	v_mfma_f32_16x16x32_bf16 v[12:15], v[136:139], v[212:215], v[12:15]
	v_mfma_f32_16x16x32_bf16 v[8:11], v[144:147], v[212:215], v[8:11]
	s_setprio 0
	s_setprio 1
	v_mfma_f32_16x16x32_bf16 v[52:55], v[148:151], v[180:183], v[52:55]
	v_mfma_f32_16x16x32_bf16 v[48:51], v[164:167], v[180:183], v[48:51]
	v_mfma_f32_16x16x32_bf16 v[36:39], v[148:151], v[188:191], v[36:39]
	v_mfma_f32_16x16x32_bf16 v[32:35], v[164:167], v[188:191], v[32:35]
	v_mfma_f32_16x16x32_bf16 v[20:23], v[148:151], v[196:199], v[20:23]
	v_mfma_f32_16x16x32_bf16 v[16:19], v[164:167], v[196:199], v[16:19]
	v_mfma_f32_16x16x32_bf16 v[4:7], v[148:151], v[208:211], v[4:7]
	v_mfma_f32_16x16x32_bf16 v[0:3], v[164:167], v[208:211], v[0:3]
	v_mfma_f32_16x16x32_bf16 v[52:55], v[152:155], v[184:187], v[52:55]
	v_mfma_f32_16x16x32_bf16 v[48:51], v[168:171], v[184:187], v[48:51]
	v_mfma_f32_16x16x32_bf16 v[36:39], v[152:155], v[192:195], v[36:39]
	v_mfma_f32_16x16x32_bf16 v[32:35], v[168:171], v[192:195], v[32:35]
	v_mfma_f32_16x16x32_bf16 v[20:23], v[152:155], v[204:207], v[20:23]
	v_mfma_f32_16x16x32_bf16 v[16:19], v[168:171], v[204:207], v[16:19]
	v_mfma_f32_16x16x32_bf16 v[4:7], v[152:155], v[212:215], v[4:7]
	v_mfma_f32_16x16x32_bf16 v[0:3], v[168:171], v[212:215], v[0:3]
	s_setprio 0
	s_barrier
	s_add_i32 s65, s65, 2
	s_add_u32 s0, s0, 0x100
	s_addc_u32 s1, s1, 0
	s_add_u32 s63, s63, 0x100
	s_addc_u32 s64, s64, 0
	s_cmp_gt_u32 s65, 13
	s_cbranch_scc0 .LBB0_613
	s_and_b64 vcc, exec, s[18:19]
	s_cbranch_vccz .LBB0_616
	s_barrier

; #define PG8_STAGE(bufoff, gbase, voff) do { _Pragma("unroll") for (int _i = 0; _i < 2; ++_i) \
;         __builtin_amdgcn_global_load_lds((const unsigned*)((const char*)(gbase) + (voff)[_i]), (PG8_LAS unsigned*)(lds + (bufoff) + ldsw + _i * 8192), 16, 0, 0); } while (0)
; #define PG8_LDA(dst, b, h) do { _Pragma("unroll") for (int m = 0; m < 4; ++m) _Pragma("unroll") for (int k = 0; k < 2; ++k) dst[m][k] = *(const PG8_LAS bf16x8*)(lds + PG8_SA(b, h) + aoff + m * 2048 + k * 1024); } while (0)
; #define PG8_LDB(dst, b, h) do { _Pragma("unroll") for (int n = 0; n < 2; ++n) _Pragma("unroll") for (int k = 0; k < 2; ++k) dst[n][k] = *(const PG8_LAS bf16x8*)(lds + PG8_SB(b, h) + boff + n * 2048 + k * 1024); } while (0)
; #define PG8_WAIT_V(n) asm volatile("s_waitcnt vmcnt(" #n ")" ::: "memory")
; #define PG8_WAIT_L(n) asm volatile("s_waitcnt lgkmcnt(" #n ")" ::: "memory")
; #define PG8_BAR __builtin_amdgcn_s_barrier()
; #define PG8_SCHED __builtin_amdgcn_sched_barrier(0)
; template <class Epi, class Sched, bool ALIGN_EPI = false, bool SP2 = false>
; __device__ __forceinline__ void gemm_phase(PG8_LAS unsigned char* lds, const Gemm g, const Sched& S, const Epi& E, const int tid_in) {
;     ...
;         const char* nA = has_next ? (const char*)g.A + (size_t)nxt.pm * tstepA + (size_t)(nxt.pm >> 3) * g.abx : cA; const char* nB = has_next ? (const char*)g.Bt + (size_t)nxt.pn * tstepB : cB;
;         for (int t = 0; t < nt; t += 2) {
;             const bool last = (t == nt - 2);
;             const char* a1 = cA + (size_t)(t + 1) * kstep;
;             const char* a2 = last ? nA : cA + (size_t)(t + 2) * kstep; const char* b2 = last ? nB : cB + (size_t)(t + 2) * kstep;
;             const char* a3 = a2 + kstep; const char* b3 = b2 + kstep;
;             if (last && has_next) S.a_ready(nxt);
;             if constexpr (SP2) {
;             PG8_LDB(B0, 0, 0); PG8_LDB(B1, 0, 1); PG8_SCHED; PG8_LDA(At, 0, 0); PG8_STAGE(PG8_SA(1, 1), a1 + hstepA, voffA);
;             PG8_WAIT_V(8); PG8_WAIT_L(0); PG8_BAR; PG8_MMA(0, 0, At, B0); PG8_MMA(0, 1, At, B1); PG8_BAR; PG8_SCHED;
;     ...
;         for (int a = 0; a < 2; ++a)
; #pragma unroll
;             for (int b = 0; b < 2; ++b)
; #pragma unroll
;                 for (int m = 0; m < 4; ++m)
; #pragma unroll
;                     for (int n = 0; n < 2; ++n) acc[a][b][m][n] = (f32x4){0.f, 0.f, 0.f, 0.f};
.LBB0_855:
	s_ashr_i32 s25, s24, 31
	s_lshl_b64 s[14:15], s[24:25], 19
	s_add_u32 s26, s43, s14
	s_addc_u32 s27, s44, s15
	s_and_b64 s[14:15], s[4:5], exec
	s_cselect_b32 s14, s27, s7
	s_cselect_b32 s15, s26, s6
	s_ashr_i32 s23, s22, 31
	s_lshl_b64 s[28:29], s[22:23], 19
	s_add_u32 s28, s45, s28
	s_addc_u32 s29, s46, s29
	s_and_b64 s[40:41], s[4:5], exec
	s_cselect_b32 s23, s29, s39
	s_cselect_b32 s25, s28, s38
	s_add_u32 s6, s6, 0x40080
	s_addc_u32 s7, s7, 0
	s_add_u32 s58, s38, 0x100
	v_mov_b32_e32 v0, 0
	s_addc_u32 s59, s39, 0
	s_mov_b32 s60, -2
	s_cmp_gt_u32 s55, 1
	s_cselect_b32 s101, 1, 0
	v_mov_b32_e32 v1, v0
	v_mov_b32_e32 v2, v0
	v_mov_b32_e32 v3, v0
	v_mov_b32_e32 v4, v0
	v_mov_b32_e32 v5, v0
	v_mov_b32_e32 v6, v0
	v_mov_b32_e32 v7, v0
	v_mov_b32_e32 v16, v0
	v_mov_b32_e32 v17, v0
	v_mov_b32_e32 v18, v0
	v_mov_b32_e32 v19, v0
	v_mov_b32_e32 v20, v0
	v_mov_b32_e32 v21, v0
	v_mov_b32_e32 v22, v0
	v_mov_b32_e32 v23, v0
	v_mov_b32_e32 v32, v0
	v_mov_b32_e32 v33, v0
	v_mov_b32_e32 v34, v0
	v_mov_b32_e32 v35, v0
	v_mov_b32_e32 v36, v0
	v_mov_b32_e32 v37, v0
	v_mov_b32_e32 v38, v0
	v_mov_b32_e32 v39, v0
	v_mov_b32_e32 v48, v0
	v_mov_b32_e32 v49, v0
	v_mov_b32_e32 v50, v0
	v_mov_b32_e32 v51, v0
	v_mov_b32_e32 v52, v0
	v_mov_b32_e32 v53, v0
	v_mov_b32_e32 v54, v0
	v_mov_b32_e32 v55, v0
	v_mov_b32_e32 v8, v0
	v_mov_b32_e32 v9, v0
	v_mov_b32_e32 v10, v0
	v_mov_b32_e32 v11, v0
	v_mov_b32_e32 v12, v0
	v_mov_b32_e32 v13, v0
	v_mov_b32_e32 v14, v0
	v_mov_b32_e32 v15, v0
	v_mov_b32_e32 v24, v0
	v_mov_b32_e32 v25, v0
	v_mov_b32_e32 v26, v0
	v_mov_b32_e32 v27, v0
	v_mov_b32_e32 v28, v0
	v_mov_b32_e32 v29, v0
	v_mov_b32_e32 v30, v0
	v_mov_b32_e32 v31, v0
	v_mov_b32_e32 v40, v0
	v_mov_b32_e32 v41, v0
	v_mov_b32_e32 v42, v0
	v_mov_b32_e32 v43, v0
	v_mov_b32_e32 v44, v0
	v_mov_b32_e32 v45, v0
	v_mov_b32_e32 v46, v0
	v_mov_b32_e32 v47, v0
	v_mov_b32_e32 v56, v0
	v_mov_b32_e32 v57, v0
	v_mov_b32_e32 v58, v0
	v_mov_b32_e32 v59, v0
	v_mov_b32_e32 v60, v0
	v_mov_b32_e32 v61, v0
	v_mov_b32_e32 v62, v0
	v_mov_b32_e32 v63, v0
	v_mov_b32_e32 v64, v0
	v_mov_b32_e32 v65, v0
	v_mov_b32_e32 v66, v0
	v_mov_b32_e32 v67, v0
	v_mov_b32_e32 v68, v0
	v_mov_b32_e32 v69, v0
	v_mov_b32_e32 v70, v0
	v_mov_b32_e32 v71, v0
	v_mov_b32_e32 v80, v0
	v_mov_b32_e32 v81, v0
	v_mov_b32_e32 v82, v0
	v_mov_b32_e32 v83, v0
	v_mov_b32_e32 v84, v0
	v_mov_b32_e32 v85, v0
	v_mov_b32_e32 v86, v0
	v_mov_b32_e32 v87, v0
	v_mov_b32_e32 v96, v0
	v_mov_b32_e32 v97, v0
	v_mov_b32_e32 v98, v0
	v_mov_b32_e32 v99, v0
	v_mov_b32_e32 v100, v0
	v_mov_b32_e32 v101, v0
	v_mov_b32_e32 v102, v0
	v_mov_b32_e32 v103, v0
	v_mov_b32_e32 v116, v0
	v_mov_b32_e32 v117, v0
	v_mov_b32_e32 v118, v0
	v_mov_b32_e32 v119, v0
	v_mov_b32_e32 v120, v0
	v_mov_b32_e32 v121, v0
	v_mov_b32_e32 v122, v0
	v_mov_b32_e32 v123, v0
	v_mov_b32_e32 v72, v0
	v_mov_b32_e32 v73, v0
	v_mov_b32_e32 v74, v0
	v_mov_b32_e32 v75, v0
	v_mov_b32_e32 v76, v0
	v_mov_b32_e32 v77, v0
	v_mov_b32_e32 v78, v0
	v_mov_b32_e32 v79, v0
	v_mov_b32_e32 v88, v0
	v_mov_b32_e32 v89, v0
	v_mov_b32_e32 v90, v0
	v_mov_b32_e32 v91, v0
	v_mov_b32_e32 v92, v0
	v_mov_b32_e32 v93, v0
	v_mov_b32_e32 v94, v0
	v_mov_b32_e32 v95, v0
	v_mov_b32_e32 v104, v0
	v_mov_b32_e32 v105, v0
	v_mov_b32_e32 v106, v0
	v_mov_b32_e32 v107, v0
	v_mov_b32_e32 v108, v0
	v_mov_b32_e32 v109, v0
	v_mov_b32_e32 v110, v0
	v_mov_b32_e32 v111, v0
	v_mov_b32_e32 v124, v0
	v_mov_b32_e32 v125, v0
	v_mov_b32_e32 v126, v0
	v_mov_b32_e32 v127, v0
	v_mov_b32_e32 v128, v0
	v_mov_b32_e32 v129, v0
	v_mov_b32_e32 v130, v0
	v_mov_b32_e32 v131, v0
.LBB0_856:
	s_add_u32 s38, s6, 0xfffc0080
	s_addc_u32 s39, s7, -1
	s_add_i32 s61, 0, 0x10000
	s_cmp_eq_u32 s60, 12
	s_cselect_b32 s41, s14, s39
	s_cselect_b32 s40, s15, s38
	s_cselect_b32 s39, s23, s59
	s_cselect_b32 s38, s25, s58
	s_add_i32 s64, 0, 0x14000
	v_add_u32_e32 v144, s61, v184
	v_add_u32_e32 v168, s64, v184
	ds_read_b128 v[132:135], v144
	ds_read_b128 v[136:139], v144 offset:1024
	ds_read_b128 v[140:143], v144 offset:2048
	ds_read_b128 v[144:147], v144 offset:3072
	ds_read_b128 v[148:151], v168
	ds_read_b128 v[152:155], v168 offset:1024
	ds_read_b128 v[164:167], v168 offset:2048
	ds_read_b128 v[168:171], v168 offset:3072
	v_lshl_add_u64 v[180:181], s[6:7], 0, v[160:161]
	s_add_i32 m0, s47, 0xc000
	ds_read_b128 v[172:175], v187
	ds_read_b128 v[176:179], v187 offset:1024
	ds_read_b128 v[188:191], v187 offset:2048
	ds_read_b128 v[192:195], v187 offset:3072
	ds_read_b128 v[196:199], v187 offset:4096
	ds_read_b128 v[200:203], v187 offset:5120
	ds_read_b128 v[204:207], v187 offset:6144
	ds_read_b128 v[208:211], v187 offset:7168
	global_load_lds_dwordx4 v[180:181], off
	v_lshl_add_u64 v[180:181], s[6:7], 0, v[162:163]
	s_add_i32 m0, s47, 0xe000
	s_nop 0
	global_load_lds_dwordx4 v[180:181], off
	s_cmp_lg_u32 s101, 0
	s_cbranch_scc1 .Lmy_rw_up_0r
	s_waitcnt vmcnt(8)
	s_branch .Lmy_rw_up_0j

; #define PG8_STAGE(bufoff, gbase, voff) do { _Pragma("unroll") for (int _i = 0; _i < 2; ++_i) \
;         __builtin_amdgcn_global_load_lds((const unsigned*)((const char*)(gbase) + (voff)[_i]), (PG8_LAS unsigned*)(lds + (bufoff) + ldsw + _i * 8192), 16, 0, 0); } while (0)
; #define PG8_LDA(dst, b, h) do { _Pragma("unroll") for (int m = 0; m < 4; ++m) _Pragma("unroll") for (int k = 0; k < 2; ++k) dst[m][k] = *(const PG8_LAS bf16x8*)(lds + PG8_SA(b, h) + aoff + m * 2048 + k * 1024); } while (0)
; #define PG8_MMA(ai, bj, At, Bt) do { __builtin_amdgcn_s_setprio(1); _Pragma("unroll") for (int m = 0; m < 4; ++m) _Pragma("unroll") for (int n = 0; n < 2; ++n) _Pragma("unroll") for (int k = 0; k < 2; ++k) \
;         acc[ai][bj][m][n] = __builtin_amdgcn_mfma_f32_16x16x32_bf16(Bt[n][k], At[m][k], acc[ai][bj][m][n], 0, 0, 0); __builtin_amdgcn_s_setprio(0); } while (0)
; #define PG8_WAIT_V(n) asm volatile("s_waitcnt vmcnt(" #n ")" ::: "memory")
; #define PG8_WAIT_L(n) asm volatile("s_waitcnt lgkmcnt(" #n ")" ::: "memory")
; #define PG8_BAR __builtin_amdgcn_s_barrier()
; #define PG8_SCHED __builtin_amdgcn_sched_barrier(0)
; template <class Epi, class Sched, bool ALIGN_EPI = false, bool SP2 = false>
; __device__ __forceinline__ void gemm_phase(PG8_LAS unsigned char* lds, const Gemm g, const Sched& S, const Epi& E, const int tid_in) {
;     ...
;             PG8_WAIT_V(8); PG8_WAIT_L(0); PG8_BAR; PG8_MMA(0, 0, At, B0); PG8_MMA(0, 1, At, B1); PG8_BAR; PG8_SCHED;
;             PG8_LDA(At, 0, 1); PG8_STAGE(PG8_SB(0, 0), b2, voffB); PG8_STAGE(PG8_SB(0, 1), b2 + hstepB, voffB); PG8_STAGE(PG8_SA(0, 0), a2, voffA);
;             PG8_WAIT_V(8); PG8_WAIT_L(0); PG8_BAR; PG8_MMA(1, 0, At, B0); PG8_MMA(1, 1, At, B1); PG8_BAR; PG8_SCHED;
.Lmy_rw_up_0j:
	s_waitcnt lgkmcnt(0)
	s_barrier
	s_setprio 1
	s_waitcnt lgkmcnt(0)
	v_mfma_f32_16x16x32_bf16 v[128:131], v[132:135], v[172:175], v[128:131]
	v_mfma_f32_16x16x32_bf16 v[124:127], v[140:143], v[172:175], v[124:127]
	v_mfma_f32_16x16x32_bf16 v[108:111], v[132:135], v[188:191], v[108:111]
	v_mfma_f32_16x16x32_bf16 v[104:107], v[140:143], v[188:191], v[104:107]
	v_mfma_f32_16x16x32_bf16 v[92:95], v[132:135], v[196:199], v[92:95]
	v_mfma_f32_16x16x32_bf16 v[88:91], v[140:143], v[196:199], v[88:91]
	v_mfma_f32_16x16x32_bf16 v[76:79], v[132:135], v[204:207], v[76:79]
	v_mfma_f32_16x16x32_bf16 v[72:75], v[140:143], v[204:207], v[72:75]
	v_mfma_f32_16x16x32_bf16 v[128:131], v[136:139], v[176:179], v[128:131]
	v_mfma_f32_16x16x32_bf16 v[124:127], v[144:147], v[176:179], v[124:127]
	v_mfma_f32_16x16x32_bf16 v[108:111], v[136:139], v[192:195], v[108:111]
	v_mfma_f32_16x16x32_bf16 v[104:107], v[144:147], v[192:195], v[104:107]
	v_mfma_f32_16x16x32_bf16 v[92:95], v[136:139], v[200:203], v[92:95]
	v_mfma_f32_16x16x32_bf16 v[88:91], v[144:147], v[200:203], v[88:91]
	v_mfma_f32_16x16x32_bf16 v[76:79], v[136:139], v[208:211], v[76:79]
	v_mfma_f32_16x16x32_bf16 v[72:75], v[144:147], v[208:211], v[72:75]
	s_setprio 0
	s_setprio 1
	v_mfma_f32_16x16x32_bf16 v[120:123], v[148:151], v[172:175], v[120:123]
	v_mfma_f32_16x16x32_bf16 v[116:119], v[164:167], v[172:175], v[116:119]
	v_mfma_f32_16x16x32_bf16 v[100:103], v[148:151], v[188:191], v[100:103]
	v_mfma_f32_16x16x32_bf16 v[96:99], v[164:167], v[188:191], v[96:99]
	v_mfma_f32_16x16x32_bf16 v[84:87], v[148:151], v[196:199], v[84:87]
	v_mfma_f32_16x16x32_bf16 v[80:83], v[164:167], v[196:199], v[80:83]
	v_mfma_f32_16x16x32_bf16 v[68:71], v[148:151], v[204:207], v[68:71]
	v_mfma_f32_16x16x32_bf16 v[64:67], v[164:167], v[204:207], v[64:67]
	v_mfma_f32_16x16x32_bf16 v[120:123], v[152:155], v[176:179], v[120:123]
	v_mfma_f32_16x16x32_bf16 v[116:119], v[168:171], v[176:179], v[116:119]
	v_mfma_f32_16x16x32_bf16 v[100:103], v[152:155], v[192:195], v[100:103]
	v_mfma_f32_16x16x32_bf16 v[96:99], v[168:171], v[192:195], v[96:99]
	v_mfma_f32_16x16x32_bf16 v[84:87], v[152:155], v[200:203], v[84:87]
	v_mfma_f32_16x16x32_bf16 v[80:83], v[168:171], v[200:203], v[80:83]
	v_mfma_f32_16x16x32_bf16 v[68:71], v[152:155], v[208:211], v[68:71]
	v_mfma_f32_16x16x32_bf16 v[64:67], v[168:171], v[208:211], v[64:67]
	s_setprio 0
	s_barrier
	s_add_i32 s61, s61, s42
	v_lshl_add_u64 v[180:181], s[38:39], 0, v[114:115]
	s_mov_b32 m0, s61
	ds_read_b128 v[172:175], v187 offset:16384
	ds_read_b128 v[176:179], v187 offset:17408
	ds_read_b128 v[188:191], v187 offset:18432
	ds_read_b128 v[192:195], v187 offset:19456
	ds_read_b128 v[196:199], v187 offset:20480
	ds_read_b128 v[200:203], v187 offset:21504
	ds_read_b128 v[204:207], v187 offset:22528
	ds_read_b128 v[208:211], v187 offset:23552
	global_load_lds_dwordx4 v[180:181], off
	s_add_i32 m0, s61, 0x2000
	s_add_u32 s62, s38, 0x40000
	v_lshl_add_u64 v[212:213], s[38:39], 0, v[158:159]
	s_addc_u32 s63, s39, 0
	s_add_i32 s61, s64, s42
	global_load_lds_dwordx4 v[212:213], off
	v_lshl_add_u64 v[214:215], s[62:63], 0, v[114:115]
	s_mov_b32 m0, s61
	v_lshl_add_u64 v[216:217], s[40:41], 0, v[156:157]
	global_load_lds_dwordx4 v[214:215], off
	v_lshl_add_u64 v[214:215], s[62:63], 0, v[158:159]
	s_add_i32 m0, s61, 0x2000
	s_nop 0
	global_load_lds_dwordx4 v[214:215], off
	v_lshl_add_u64 v[214:215], s[40:41], 0, v[112:113]
	s_mov_b32 m0, s47
	s_nop 0
	global_load_lds_dwordx4 v[214:215], off
	s_mov_b32 m0, s50
	s_nop 0
	global_load_lds_dwordx4 v[216:217], off
	s_cmp_lg_u32 s101, 0
	s_cbranch_scc1 .Lmy_rw_up_1r
	s_waitcnt vmcnt(8)
	s_branch .Lmy_rw_up_1j

; #define PG8_STAGE(bufoff, gbase, voff) do { _Pragma("unroll") for (int _i = 0; _i < 2; ++_i) \
;         __builtin_amdgcn_global_load_lds((const unsigned*)((const char*)(gbase) + (voff)[_i]), (PG8_LAS unsigned*)(lds + (bufoff) + ldsw + _i * 8192), 16, 0, 0); } while (0)
; #define PG8_LDA(dst, b, h) do { _Pragma("unroll") for (int m = 0; m < 4; ++m) _Pragma("unroll") for (int k = 0; k < 2; ++k) dst[m][k] = *(const PG8_LAS bf16x8*)(lds + PG8_SA(b, h) + aoff + m * 2048 + k * 1024); } while (0)
; #define PG8_LDB(dst, b, h) do { _Pragma("unroll") for (int n = 0; n < 2; ++n) _Pragma("unroll") for (int k = 0; k < 2; ++k) dst[n][k] = *(const PG8_LAS bf16x8*)(lds + PG8_SB(b, h) + boff + n * 2048 + k * 1024); } while (0)
; #define PG8_MMA(ai, bj, At, Bt) do { __builtin_amdgcn_s_setprio(1); _Pragma("unroll") for (int m = 0; m < 4; ++m) _Pragma("unroll") for (int n = 0; n < 2; ++n) _Pragma("unroll") for (int k = 0; k < 2; ++k) \
;         acc[ai][bj][m][n] = __builtin_amdgcn_mfma_f32_16x16x32_bf16(Bt[n][k], At[m][k], acc[ai][bj][m][n], 0, 0, 0); __builtin_amdgcn_s_setprio(0); } while (0)
; #define PG8_WAIT_V(n) asm volatile("s_waitcnt vmcnt(" #n ")" ::: "memory")
; #define PG8_WAIT_L(n) asm volatile("s_waitcnt lgkmcnt(" #n ")" ::: "memory")
; #define PG8_BAR __builtin_amdgcn_s_barrier()
; #define PG8_SCHED __builtin_amdgcn_sched_barrier(0)
; template <class Epi, class Sched, bool ALIGN_EPI = false, bool SP2 = false>
; __device__ __forceinline__ void gemm_phase(PG8_LAS unsigned char* lds, const Gemm g, const Sched& S, const Epi& E, const int tid_in) {
;     ...
;             PG8_WAIT_V(8); PG8_WAIT_L(0); PG8_BAR; PG8_MMA(1, 0, At, B0); PG8_MMA(1, 1, At, B1); PG8_BAR; PG8_SCHED;
;             PG8_LDB(B0, 1, 0); PG8_LDB(B1, 1, 1); PG8_SCHED; PG8_LDA(At, 1, 0); PG8_STAGE(PG8_SA(0, 1), a2 + hstepA, voffA);
;             PG8_WAIT_V(8); PG8_WAIT_L(0); PG8_BAR; PG8_MMA(0, 0, At, B0); PG8_MMA(0, 1, At, B1); PG8_BAR; PG8_SCHED;
.Lmy_rw_up_1j:
	s_mov_b32 s101, 0
	s_waitcnt lgkmcnt(0)
	s_barrier
	s_setprio 1
	s_waitcnt lgkmcnt(0)
	v_mfma_f32_16x16x32_bf16 v[60:63], v[132:135], v[172:175], v[60:63]
	v_mfma_f32_16x16x32_bf16 v[56:59], v[140:143], v[172:175], v[56:59]
	v_mfma_f32_16x16x32_bf16 v[44:47], v[132:135], v[188:191], v[44:47]
	v_mfma_f32_16x16x32_bf16 v[40:43], v[140:143], v[188:191], v[40:43]
	v_mfma_f32_16x16x32_bf16 v[28:31], v[132:135], v[196:199], v[28:31]
	v_mfma_f32_16x16x32_bf16 v[24:27], v[140:143], v[196:199], v[24:27]
	v_mfma_f32_16x16x32_bf16 v[12:15], v[132:135], v[204:207], v[12:15]
	v_mfma_f32_16x16x32_bf16 v[8:11], v[140:143], v[204:207], v[8:11]
	v_mfma_f32_16x16x32_bf16 v[60:63], v[136:139], v[176:179], v[60:63]
	v_mfma_f32_16x16x32_bf16 v[56:59], v[144:147], v[176:179], v[56:59]
	v_mfma_f32_16x16x32_bf16 v[44:47], v[136:139], v[192:195], v[44:47]
	v_mfma_f32_16x16x32_bf16 v[40:43], v[144:147], v[192:195], v[40:43]
	v_mfma_f32_16x16x32_bf16 v[28:31], v[136:139], v[200:203], v[28:31]
	v_mfma_f32_16x16x32_bf16 v[24:27], v[144:147], v[200:203], v[24:27]
	v_mfma_f32_16x16x32_bf16 v[12:15], v[136:139], v[208:211], v[12:15]
	v_mfma_f32_16x16x32_bf16 v[8:11], v[144:147], v[208:211], v[8:11]
	s_setprio 0
	s_setprio 1
	v_mfma_f32_16x16x32_bf16 v[52:55], v[148:151], v[172:175], v[52:55]
	v_mfma_f32_16x16x32_bf16 v[48:51], v[164:167], v[172:175], v[48:51]
	v_mfma_f32_16x16x32_bf16 v[36:39], v[148:151], v[188:191], v[36:39]
	v_mfma_f32_16x16x32_bf16 v[32:35], v[164:167], v[188:191], v[32:35]
	v_mfma_f32_16x16x32_bf16 v[20:23], v[148:151], v[196:199], v[20:23]
	v_mfma_f32_16x16x32_bf16 v[16:19], v[164:167], v[196:199], v[16:19]
	v_mfma_f32_16x16x32_bf16 v[4:7], v[148:151], v[204:207], v[4:7]
	v_mfma_f32_16x16x32_bf16 v[0:3], v[164:167], v[204:207], v[0:3]
	v_mfma_f32_16x16x32_bf16 v[52:55], v[152:155], v[176:179], v[52:55]
	v_mfma_f32_16x16x32_bf16 v[48:51], v[168:171], v[176:179], v[48:51]
	v_mfma_f32_16x16x32_bf16 v[36:39], v[152:155], v[192:195], v[36:39]
	v_mfma_f32_16x16x32_bf16 v[32:35], v[168:171], v[192:195], v[32:35]
	v_mfma_f32_16x16x32_bf16 v[20:23], v[152:155], v[200:203], v[20:23]
	v_mfma_f32_16x16x32_bf16 v[16:19], v[168:171], v[200:203], v[16:19]
	v_mfma_f32_16x16x32_bf16 v[4:7], v[152:155], v[208:211], v[4:7]
	v_mfma_f32_16x16x32_bf16 v[0:3], v[168:171], v[208:211], v[0:3]
	s_setprio 0
	s_barrier
	s_add_i32 s61, 0, 0x18000
	s_add_i32 s62, 0, 0x1c000
	v_add_u32_e32 v144, s61, v184
	v_add_u32_e32 v168, s62, v184
	ds_read_b128 v[132:135], v144
	ds_read_b128 v[136:139], v144 offset:1024
	ds_read_b128 v[140:143], v144 offset:2048
	ds_read_b128 v[144:147], v144 offset:3072
	ds_read_b128 v[148:151], v168
	ds_read_b128 v[152:155], v168 offset:1024
	ds_read_b128 v[164:167], v168 offset:2048
	ds_read_b128 v[168:171], v168 offset:3072
	s_add_u32 s40, s40, 0x40000
	s_addc_u32 s41, s41, 0
	s_mov_b32 m0, s51
	v_lshl_add_u64 v[218:219], s[40:41], 0, v[112:113]
	ds_read_b128 v[172:175], v187 offset:32768
	ds_read_b128 v[176:179], v187 offset:33792
	ds_read_b128 v[188:191], v187 offset:34816
	ds_read_b128 v[192:195], v187 offset:35840
	ds_read_b128 v[196:199], v187 offset:36864
	ds_read_b128 v[200:203], v187 offset:37888
	ds_read_b128 v[204:207], v187 offset:38912
	ds_read_b128 v[208:211], v187 offset:39936
	global_load_lds_dwordx4 v[218:219], off
	v_lshl_add_u64 v[218:219], s[40:41], 0, v[156:157]
	s_mov_b32 m0, s52
	s_nop 0
	global_load_lds_dwordx4 v[218:219], off
	s_waitcnt vmcnt(8)
	s_waitcnt lgkmcnt(0)
	s_barrier
	s_setprio 1
	s_waitcnt lgkmcnt(0)
	v_mfma_f32_16x16x32_bf16 v[128:131], v[132:135], v[172:175], v[128:131]
	v_mfma_f32_16x16x32_bf16 v[124:127], v[140:143], v[172:175], v[124:127]
	v_mfma_f32_16x16x32_bf16 v[108:111], v[132:135], v[188:191], v[108:111]
	v_mfma_f32_16x16x32_bf16 v[104:107], v[140:143], v[188:191], v[104:107]
	v_mfma_f32_16x16x32_bf16 v[92:95], v[132:135], v[196:199], v[92:95]
	v_mfma_f32_16x16x32_bf16 v[88:91], v[140:143], v[196:199], v[88:91]
	v_mfma_f32_16x16x32_bf16 v[76:79], v[132:135], v[204:207], v[76:79]
	v_mfma_f32_16x16x32_bf16 v[72:75], v[140:143], v[204:207], v[72:75]
	v_mfma_f32_16x16x32_bf16 v[128:131], v[136:139], v[176:179], v[128:131]
	v_mfma_f32_16x16x32_bf16 v[124:127], v[144:147], v[176:179], v[124:127]
	v_mfma_f32_16x16x32_bf16 v[108:111], v[136:139], v[192:195], v[108:111]
	v_mfma_f32_16x16x32_bf16 v[104:107], v[144:147], v[192:195], v[104:107]
	v_mfma_f32_16x16x32_bf16 v[92:95], v[136:139], v[200:203], v[92:95]
	v_mfma_f32_16x16x32_bf16 v[88:91], v[144:147], v[200:203], v[88:91]
	v_mfma_f32_16x16x32_bf16 v[76:79], v[136:139], v[208:211], v[76:79]
	v_mfma_f32_16x16x32_bf16 v[72:75], v[144:147], v[208:211], v[72:75]
	s_setprio 0
	s_setprio 1
	v_mfma_f32_16x16x32_bf16 v[120:123], v[148:151], v[172:175], v[120:123]
	v_mfma_f32_16x16x32_bf16 v[116:119], v[164:167], v[172:175], v[116:119]
	v_mfma_f32_16x16x32_bf16 v[100:103], v[148:151], v[188:191], v[100:103]
	v_mfma_f32_16x16x32_bf16 v[96:99], v[164:167], v[188:191], v[96:99]
	v_mfma_f32_16x16x32_bf16 v[84:87], v[148:151], v[196:199], v[84:87]
	v_mfma_f32_16x16x32_bf16 v[80:83], v[164:167], v[196:199], v[80:83]
	v_mfma_f32_16x16x32_bf16 v[68:71], v[148:151], v[204:207], v[68:71]
	v_mfma_f32_16x16x32_bf16 v[64:67], v[164:167], v[204:207], v[64:67]
	v_mfma_f32_16x16x32_bf16 v[120:123], v[152:155], v[176:179], v[120:123]
	v_mfma_f32_16x16x32_bf16 v[116:119], v[168:171], v[176:179], v[116:119]
	v_mfma_f32_16x16x32_bf16 v[100:103], v[152:155], v[192:195], v[100:103]
	v_mfma_f32_16x16x32_bf16 v[96:99], v[168:171], v[192:195], v[96:99]
	v_mfma_f32_16x16x32_bf16 v[84:87], v[152:155], v[200:203], v[84:87]
	v_mfma_f32_16x16x32_bf16 v[80:83], v[168:171], v[200:203], v[80:83]
	v_mfma_f32_16x16x32_bf16 v[68:71], v[152:155], v[208:211], v[68:71]
	v_mfma_f32_16x16x32_bf16 v[64:67], v[168:171], v[208:211], v[64:67]
	s_setprio 0
	s_barrier
; #define PG8_STAGE(bufoff, gbase, voff) do { _Pragma("unroll") for (int _i = 0; _i < 2; ++_i) \
;         __builtin_amdgcn_global_load_lds((const unsigned*)((const char*)(gbase) + (voff)[_i]), (PG8_LAS unsigned*)(lds + (bufoff) + ldsw + _i * 8192), 16, 0, 0); } while (0)
; #define PG8_LDA(dst, b, h) do { _Pragma("unroll") for (int m = 0; m < 4; ++m) _Pragma("unroll") for (int k = 0; k < 2; ++k) dst[m][k] = *(const PG8_LAS bf16x8*)(lds + PG8_SA(b, h) + aoff + m * 2048 + k * 1024); } while (0)
; #define PG8_MMA(ai, bj, At, Bt) do { __builtin_amdgcn_s_setprio(1); _Pragma("unroll") for (int m = 0; m < 4; ++m) _Pragma("unroll") for (int n = 0; n < 2; ++n) _Pragma("unroll") for (int k = 0; k < 2; ++k) \
;         acc[ai][bj][m][n] = __builtin_amdgcn_mfma_f32_16x16x32_bf16(Bt[n][k], At[m][k], acc[ai][bj][m][n], 0, 0, 0); __builtin_amdgcn_s_setprio(0); } while (0)
; #define PG8_WAIT_V(n) asm volatile("s_waitcnt vmcnt(" #n ")" ::: "memory")
; #define PG8_WAIT_L(n) asm volatile("s_waitcnt lgkmcnt(" #n ")" ::: "memory")
; #define PG8_BAR __builtin_amdgcn_s_barrier()
; #define PG8_SCHED __builtin_amdgcn_sched_barrier(0)
; template <class Epi, class Sched, bool ALIGN_EPI = false, bool SP2 = false>
; __device__ __forceinline__ void gemm_phase(PG8_LAS unsigned char* lds, const Gemm g, const Sched& S, const Epi& E, const int tid_in) {
;     ...
;             PG8_LDA(At, 1, 1); PG8_STAGE(PG8_SB(1, 0), b3, voffB); PG8_STAGE(PG8_SB(1, 1), b3 + hstepB, voffB); PG8_STAGE(PG8_SA(1, 0), a3, voffA);
;             PG8_WAIT_V(8); PG8_WAIT_L(0); PG8_BAR; PG8_MMA(1, 0, At, B0); PG8_MMA(1, 1, At, B1); PG8_BAR; PG8_SCHED;
	s_add_i32 s40, s61, s42
	v_lshl_add_u64 v[180:181], v[180:181], 0, s[10:11]
	s_mov_b32 m0, s40
	ds_read_b128 v[172:175], v187 offset:49152
	ds_read_b128 v[176:179], v187 offset:50176
	ds_read_b128 v[188:191], v187 offset:51200
	ds_read_b128 v[192:195], v187 offset:52224
	ds_read_b128 v[196:199], v187 offset:53248
	ds_read_b128 v[200:203], v187 offset:54272
	ds_read_b128 v[204:207], v187 offset:55296
	ds_read_b128 v[208:211], v187 offset:56320
	global_load_lds_dwordx4 v[180:181], off
	s_add_i32 m0, s40, 0x2000
	s_add_u32 s38, s38, 0x40080
	v_lshl_add_u64 v[180:181], v[212:213], 0, s[10:11]
	s_addc_u32 s39, s39, 0
	s_add_i32 s40, s62, s42
	global_load_lds_dwordx4 v[180:181], off
	v_lshl_add_u64 v[180:181], s[38:39], 0, v[114:115]
	s_mov_b32 m0, s40
	s_nop 0
	global_load_lds_dwordx4 v[180:181], off
	v_lshl_add_u64 v[180:181], s[38:39], 0, v[158:159]
	s_add_i32 m0, s40, 0x2000
	s_nop 0
	global_load_lds_dwordx4 v[180:181], off
	v_lshl_add_u64 v[180:181], v[214:215], 0, s[10:11]
	s_mov_b32 m0, s53
	s_nop 0
	global_load_lds_dwordx4 v[180:181], off
	v_lshl_add_u64 v[180:181], v[216:217], 0, s[10:11]
	s_mov_b32 m0, s54
	s_nop 0
	global_load_lds_dwordx4 v[180:181], off
	s_waitcnt vmcnt(8)
	s_waitcnt lgkmcnt(0)
	s_barrier
	s_setprio 1
	s_waitcnt lgkmcnt(0)
	v_mfma_f32_16x16x32_bf16 v[60:63], v[132:135], v[172:175], v[60:63]
	v_mfma_f32_16x16x32_bf16 v[56:59], v[140:143], v[172:175], v[56:59]
	v_mfma_f32_16x16x32_bf16 v[44:47], v[132:135], v[188:191], v[44:47]
	v_mfma_f32_16x16x32_bf16 v[40:43], v[140:143], v[188:191], v[40:43]
	v_mfma_f32_16x16x32_bf16 v[28:31], v[132:135], v[196:199], v[28:31]
	v_mfma_f32_16x16x32_bf16 v[24:27], v[140:143], v[196:199], v[24:27]
	v_mfma_f32_16x16x32_bf16 v[12:15], v[132:135], v[204:207], v[12:15]
	v_mfma_f32_16x16x32_bf16 v[8:11], v[140:143], v[204:207], v[8:11]
	v_mfma_f32_16x16x32_bf16 v[60:63], v[136:139], v[176:179], v[60:63]
	v_mfma_f32_16x16x32_bf16 v[56:59], v[144:147], v[176:179], v[56:59]
	v_mfma_f32_16x16x32_bf16 v[44:47], v[136:139], v[192:195], v[44:47]
	v_mfma_f32_16x16x32_bf16 v[40:43], v[144:147], v[192:195], v[40:43]
	v_mfma_f32_16x16x32_bf16 v[28:31], v[136:139], v[200:203], v[28:31]
	v_mfma_f32_16x16x32_bf16 v[24:27], v[144:147], v[200:203], v[24:27]
	v_mfma_f32_16x16x32_bf16 v[12:15], v[136:139], v[208:211], v[12:15]
	v_mfma_f32_16x16x32_bf16 v[8:11], v[144:147], v[208:211], v[8:11]
	s_setprio 0
	s_setprio 1
	v_mfma_f32_16x16x32_bf16 v[52:55], v[148:151], v[172:175], v[52:55]
	v_mfma_f32_16x16x32_bf16 v[48:51], v[164:167], v[172:175], v[48:51]
	v_mfma_f32_16x16x32_bf16 v[36:39], v[148:151], v[188:191], v[36:39]
	v_mfma_f32_16x16x32_bf16 v[32:35], v[164:167], v[188:191], v[32:35]
	v_mfma_f32_16x16x32_bf16 v[20:23], v[148:151], v[196:199], v[20:23]
	v_mfma_f32_16x16x32_bf16 v[16:19], v[164:167], v[196:199], v[16:19]
	v_mfma_f32_16x16x32_bf16 v[4:7], v[148:151], v[204:207], v[4:7]
	v_mfma_f32_16x16x32_bf16 v[0:3], v[164:167], v[204:207], v[0:3]
	v_mfma_f32_16x16x32_bf16 v[52:55], v[152:155], v[176:179], v[52:55]
	v_mfma_f32_16x16x32_bf16 v[48:51], v[168:171], v[176:179], v[48:51]
	v_mfma_f32_16x16x32_bf16 v[36:39], v[152:155], v[192:195], v[36:39]
	v_mfma_f32_16x16x32_bf16 v[32:35], v[168:171], v[192:195], v[32:35]
	v_mfma_f32_16x16x32_bf16 v[20:23], v[152:155], v[200:203], v[20:23]
	v_mfma_f32_16x16x32_bf16 v[16:19], v[168:171], v[200:203], v[16:19]
	v_mfma_f32_16x16x32_bf16 v[4:7], v[152:155], v[208:211], v[4:7]
	v_mfma_f32_16x16x32_bf16 v[0:3], v[168:171], v[208:211], v[0:3]
	s_setprio 0
	s_barrier
	s_add_i32 s60, s60, 2
	s_add_u32 s6, s6, 0x100
	s_addc_u32 s7, s7, 0
	s_add_u32 s58, s58, 0x100
	s_addc_u32 s59, s59, 0
	s_cmp_gt_u32 s60, 13
	s_cbranch_scc0 .LBB0_856
	s_and_b64 vcc, exec, s[20:21]
	s_cbranch_vccz .LBB0_859
	s_barrier
